# GEMM K-loops: both 6-piece load segments reduced to 5 pieces (second one's weight piece deferred to the next iteration's first segment via a saved address); 5+3+5+3 per iteration
# baseline (speedup 1.0000x reference)
.LBB0_312:
	s_add_u32 s22, s14, 0x200000
	s_addc_u32 s23, s15, 0
	s_add_u32 s24, s14, 0x300000
	s_addc_u32 s25, s15, 0
	s_add_u32 s26, s14, 0x4800000
	s_addc_u32 s27, s15, 0
	s_add_u32 s28, s14, 0x8800000
	s_addc_u32 s29, s15, 0
	s_add_u32 s30, s14, 0xc800000
	s_addc_u32 s31, s15, 0
	s_add_u32 s14, s14, 0x14800000
	s_addc_u32 s15, s15, 0
	s_lshl_b32 s65, s4, 6
	s_lshl_b32 s66, s4, 13
	s_lshl_b32 s4, s5, 5
	s_mov_b64 s[36:37], 0x80
	s_and_b32 s67, s4, 0x60
	s_add_i32 m0, s17, 0x18000
	v_lshl_add_u64 v[6:7], v[6:7], 0, s[36:37]
	s_lshl_b32 s38, s67, 7
	s_waitcnt vmcnt(2)
	s_barrier
	global_load_lds_dwordx4 v[6:7], off
	v_lshl_add_u64 v[4:5], v[4:5], 0, s[36:37]
	s_add_i32 m0, s17, 0x1a000
	s_add_i32 s68, s17, 0x8000
	s_add_i32 s69, s17, 0xa000
	global_load_lds_dwordx4 v[4:5], off
	v_lshl_add_u64 v[0:1], v[0:1], 0, s[36:37]
	s_mov_b32 m0, s68
	s_add_u32 s4, s8, 0x40080
	global_load_lds_dwordx4 v[0:1], off
	v_lshl_add_u64 v[0:1], v[2:3], 0, s[36:37]
	s_mov_b32 m0, s69
	s_addc_u32 s5, s9, 0
	global_load_lds_dwordx4 v[0:1], off
	s_add_i32 m0, s17, 0x1c000
	v_lshl_add_u64 v[0:1], s[4:5], 0, v[162:163]
	global_load_lds_dwordx4 v[0:1], off
	v_lshl_add_u64 v[0:1], s[4:5], 0, v[166:167]
	s_add_i32 m0, s17, 0x1e000
	s_movk_i32 s4, 0x3c0
	global_load_lds_dwordx4 v[0:1], off
	v_mov_b32_e32 v254, v0
	v_mov_b32_e32 v255, v1
	s_add_i32 s99, s17, 0x1e000
	v_and_b32_e32 v0, 48, v8
	v_lshlrev_b32_e32 v1, 6, v8
	v_and_or_b32 v0, v1, s4, v0
	v_lshlrev_b32_e32 v1, 2, v8
	v_and_b32_e32 v1, 32, v1
	v_bitop3_b32 v2, v0, s66, v1 bitop3:0xde
	v_bitop3_b32 v208, s38, v0, v1 bitop3:0xf6
	v_lshlrev_b32_e32 v0, 14, v9
	v_and_b32_e32 v0, 0xffff8000, v0
	v_lshl_add_u32 v0, v10, 11, v0
	v_and_b32_e32 v1, 1, v9
	v_lshl_or_b32 v0, v1, 6, v0
	v_lshl_add_u32 v170, v11, 1, v0
	v_lshlrev_b32_e32 v0, 14, v12
	v_and_b32_e32 v0, 0xffff8000, v0
	s_waitcnt vmcnt(6)
	s_cmpk_lt_u32 s18, 0x100
	v_lshl_add_u32 v0, v13, 11, v0
	v_and_b32_e32 v1, 1, v12
	s_cselect_b64 s[38:39], -1, 0
	v_lshl_or_b32 v0, v1, 6, v0
	s_add_i32 s73, 0, 0x10000
	s_add_i32 s74, 0, 0x14000
	s_movk_i32 s40, 0xe000
	s_add_i32 s70, s66, 0x4000
	s_ashr_i32 s71, s58, 31
	v_mov_b32_e32 v171, v169
	v_lshl_add_u32 v172, v14, 1, v0
	v_mov_b32_e32 v173, v169
	v_mov_b64_e32 v[174:175], 0xc00
	v_mov_b64_e32 v[176:177], 0xbff
	s_movk_i32 s72, 0x181
	v_add_u32_e32 v209, s73, v208
	v_add_u32_e32 v210, s74, v208
	v_add_u32_e32 v211, 0, v2
	v_mov_b32_e32 v212, 0x358637bd
	s_mov_b32 s41, -1
	s_movk_i32 s75, 0xe000
	s_mov_b32 s76, 0xc2fc0000
	v_mov_b32_e32 v213, 0xbbb906ce
	v_mov_b32_e32 v214, 0xbc3963dd
	v_mov_b32_e32 v215, 0x42800000
	v_not_b32_e32 v216, 63
	s_mov_b32 s5, 0
	s_barrier
	s_branch .LBB0_315

.LBB0_323:
	s_mov_b32 m0, s99
	s_nop 0
	global_load_lds_dwordx4 v[254:255], off
	ds_read_b128 v[96:99], v209
	ds_read_b128 v[100:103], v209 offset:1024
	ds_read_b128 v[120:123], v209 offset:2048
	ds_read_b128 v[124:127], v209 offset:3072
	ds_read_b128 v[144:147], v210
	ds_read_b128 v[148:151], v210 offset:1024
	ds_read_b128 v[152:155], v210 offset:2048
	ds_read_b128 v[156:159], v210 offset:3072
	s_add_u32 s8, s6, 0xfffc0080
	s_addc_u32 s9, s7, -1
	s_cmp_eq_u32 s78, 12
	s_cselect_b32 s51, s18, s9
	s_cselect_b32 s50, s43, s8
	s_cselect_b32 s9, s45, s57
	s_cselect_b32 s8, s55, s56
	v_lshl_add_u64 v[206:207], s[6:7], 0, v[170:171]
	s_add_i32 m0, s17, 0xc000
	ds_read_b128 v[178:181], v211
	ds_read_b128 v[182:185], v211 offset:1024
	ds_read_b128 v[186:189], v211 offset:2048
	ds_read_b128 v[190:193], v211 offset:3072
	ds_read_b128 v[194:197], v211 offset:4096
	ds_read_b128 v[198:201], v211 offset:5120
	ds_read_b128 v[202:205], v211 offset:6144
	ds_read_b128 v[218:221], v211 offset:7168
	global_load_lds_dwordx4 v[206:207], off
	v_lshl_add_u64 v[206:207], s[6:7], 0, v[172:173]
	s_add_i32 m0, s17, 0xe000
	s_nop 0
	global_load_lds_dwordx4 v[206:207], off
	s_waitcnt vmcnt(8)
	s_waitcnt lgkmcnt(0)
	s_barrier
	s_setprio 1
	s_waitcnt lgkmcnt(0)
	v_mfma_f32_16x16x32_bf16 v[140:143], v[96:99], v[178:181], v[140:143]
	v_mfma_f32_16x16x32_bf16 v[136:139], v[120:123], v[178:181], v[136:139]
	v_mfma_f32_16x16x32_bf16 v[116:119], v[96:99], v[186:189], v[116:119]
	v_mfma_f32_16x16x32_bf16 v[112:115], v[120:123], v[186:189], v[112:115]
	v_mfma_f32_16x16x32_bf16 v[92:95], v[96:99], v[194:197], v[92:95]
	v_mfma_f32_16x16x32_bf16 v[88:91], v[120:123], v[194:197], v[88:91]
	v_mfma_f32_16x16x32_bf16 v[76:79], v[96:99], v[202:205], v[76:79]
	v_mfma_f32_16x16x32_bf16 v[72:75], v[120:123], v[202:205], v[72:75]
	v_mfma_f32_16x16x32_bf16 v[140:143], v[100:103], v[182:185], v[140:143]
	v_mfma_f32_16x16x32_bf16 v[136:139], v[124:127], v[182:185], v[136:139]
	v_mfma_f32_16x16x32_bf16 v[116:119], v[100:103], v[190:193], v[116:119]
	v_mfma_f32_16x16x32_bf16 v[112:115], v[124:127], v[190:193], v[112:115]
	v_mfma_f32_16x16x32_bf16 v[92:95], v[100:103], v[198:201], v[92:95]
	v_mfma_f32_16x16x32_bf16 v[88:91], v[124:127], v[198:201], v[88:91]
	v_mfma_f32_16x16x32_bf16 v[76:79], v[100:103], v[218:221], v[76:79]
	v_mfma_f32_16x16x32_bf16 v[72:75], v[124:127], v[218:221], v[72:75]
	s_setprio 0
	s_setprio 1
	v_mfma_f32_16x16x32_bf16 v[132:135], v[144:147], v[178:181], v[132:135]
	v_mfma_f32_16x16x32_bf16 v[128:131], v[152:155], v[178:181], v[128:131]
	v_mfma_f32_16x16x32_bf16 v[108:111], v[144:147], v[186:189], v[108:111]
	v_mfma_f32_16x16x32_bf16 v[104:107], v[152:155], v[186:189], v[104:107]
	v_mfma_f32_16x16x32_bf16 v[84:87], v[144:147], v[194:197], v[84:87]
	v_mfma_f32_16x16x32_bf16 v[80:83], v[152:155], v[194:197], v[80:83]
	v_mfma_f32_16x16x32_bf16 v[68:71], v[144:147], v[202:205], v[68:71]
	v_mfma_f32_16x16x32_bf16 v[64:67], v[152:155], v[202:205], v[64:67]
	v_mfma_f32_16x16x32_bf16 v[132:135], v[148:151], v[182:185], v[132:135]
	v_mfma_f32_16x16x32_bf16 v[128:131], v[156:159], v[182:185], v[128:131]
	v_mfma_f32_16x16x32_bf16 v[108:111], v[148:151], v[190:193], v[108:111]
	v_mfma_f32_16x16x32_bf16 v[104:107], v[156:159], v[190:193], v[104:107]
	s_setprio 2
	s_barrier
	v_mfma_f32_16x16x32_bf16 v[84:87], v[148:151], v[198:201], v[84:87]
	v_mfma_f32_16x16x32_bf16 v[80:83], v[156:159], v[198:201], v[80:83]
	v_mfma_f32_16x16x32_bf16 v[68:71], v[148:151], v[218:221], v[68:71]
	v_mfma_f32_16x16x32_bf16 v[64:67], v[156:159], v[218:221], v[64:67]
	s_setprio 0
	s_add_i32 s79, s73, s61
	v_lshl_add_u64 v[206:207], s[8:9], 0, v[162:163]
	s_mov_b32 m0, s79
	ds_read_b128 v[178:181], v211 offset:16384
	ds_read_b128 v[182:185], v211 offset:17408
	ds_read_b128 v[186:189], v211 offset:18432
	ds_read_b128 v[190:193], v211 offset:19456
	ds_read_b128 v[194:197], v211 offset:20480
	ds_read_b128 v[198:201], v211 offset:21504
	ds_read_b128 v[202:205], v211 offset:22528
	ds_read_b128 v[218:221], v211 offset:23552
	global_load_lds_dwordx4 v[206:207], off
	s_add_i32 m0, s79, 0x2000
	s_add_u32 s80, s8, 0x40000
	v_lshl_add_u64 v[222:223], s[8:9], 0, v[166:167]
	s_addc_u32 s81, s9, 0
	s_add_i32 s79, s74, s61
	global_load_lds_dwordx4 v[222:223], off
	v_lshl_add_u64 v[224:225], s[80:81], 0, v[162:163]
	s_mov_b32 m0, s79
	v_lshl_add_u64 v[226:227], s[50:51], 0, v[164:165]
	global_load_lds_dwordx4 v[224:225], off
	v_lshl_add_u64 v[224:225], s[50:51], 0, v[160:161]
	s_mov_b32 m0, s17
	s_nop 0
	global_load_lds_dwordx4 v[224:225], off
	s_mov_b32 m0, s62
	s_nop 0
	global_load_lds_dwordx4 v[226:227], off
	s_waitcnt vmcnt(7)
	s_waitcnt lgkmcnt(0)
	s_barrier
	s_setprio 1
	s_waitcnt lgkmcnt(0)
	v_mfma_f32_16x16x32_bf16 v[60:63], v[96:99], v[178:181], v[60:63]
	v_mfma_f32_16x16x32_bf16 v[56:59], v[120:123], v[178:181], v[56:59]
	v_mfma_f32_16x16x32_bf16 v[44:47], v[96:99], v[186:189], v[44:47]
	v_mfma_f32_16x16x32_bf16 v[40:43], v[120:123], v[186:189], v[40:43]
	v_mfma_f32_16x16x32_bf16 v[28:31], v[96:99], v[194:197], v[28:31]
	v_mfma_f32_16x16x32_bf16 v[24:27], v[120:123], v[194:197], v[24:27]
	v_mfma_f32_16x16x32_bf16 v[12:15], v[96:99], v[202:205], v[12:15]
	v_mfma_f32_16x16x32_bf16 v[8:11], v[120:123], v[202:205], v[8:11]
	v_mfma_f32_16x16x32_bf16 v[60:63], v[100:103], v[182:185], v[60:63]
	v_mfma_f32_16x16x32_bf16 v[56:59], v[124:127], v[182:185], v[56:59]
	v_mfma_f32_16x16x32_bf16 v[44:47], v[100:103], v[190:193], v[44:47]
	v_mfma_f32_16x16x32_bf16 v[40:43], v[124:127], v[190:193], v[40:43]
	v_mfma_f32_16x16x32_bf16 v[28:31], v[100:103], v[198:201], v[28:31]
	v_mfma_f32_16x16x32_bf16 v[24:27], v[124:127], v[198:201], v[24:27]
	v_mfma_f32_16x16x32_bf16 v[12:15], v[100:103], v[218:221], v[12:15]
	v_mfma_f32_16x16x32_bf16 v[8:11], v[124:127], v[218:221], v[8:11]
	s_setprio 0
	s_setprio 1
	v_mfma_f32_16x16x32_bf16 v[52:55], v[144:147], v[178:181], v[52:55]
	v_mfma_f32_16x16x32_bf16 v[48:51], v[152:155], v[178:181], v[48:51]
	v_mfma_f32_16x16x32_bf16 v[36:39], v[144:147], v[186:189], v[36:39]
	v_mfma_f32_16x16x32_bf16 v[32:35], v[152:155], v[186:189], v[32:35]
	v_mfma_f32_16x16x32_bf16 v[20:23], v[144:147], v[194:197], v[20:23]
	v_mfma_f32_16x16x32_bf16 v[16:19], v[152:155], v[194:197], v[16:19]
	v_mfma_f32_16x16x32_bf16 v[4:7], v[144:147], v[202:205], v[4:7]
	v_mfma_f32_16x16x32_bf16 v[0:3], v[152:155], v[202:205], v[0:3]
	v_mfma_f32_16x16x32_bf16 v[52:55], v[148:151], v[182:185], v[52:55]
	v_mfma_f32_16x16x32_bf16 v[48:51], v[156:159], v[182:185], v[48:51]
	v_mfma_f32_16x16x32_bf16 v[36:39], v[148:151], v[190:193], v[36:39]
	v_mfma_f32_16x16x32_bf16 v[32:35], v[156:159], v[190:193], v[32:35]
	s_setprio 2
	s_barrier
	v_mfma_f32_16x16x32_bf16 v[20:23], v[148:151], v[198:201], v[20:23]
	v_mfma_f32_16x16x32_bf16 v[16:19], v[156:159], v[198:201], v[16:19]
	v_mfma_f32_16x16x32_bf16 v[4:7], v[148:151], v[218:221], v[4:7]
	v_mfma_f32_16x16x32_bf16 v[0:3], v[156:159], v[218:221], v[0:3]
	s_setprio 0
	v_lshl_add_u64 v[252:253], s[80:81], 0, v[166:167]
	s_add_i32 m0, s79, 0x2000
	s_nop 0
	global_load_lds_dwordx4 v[252:253], off
	s_add_i32 s79, 0, 0x18000
	s_add_i32 s80, 0, 0x1c000
	v_add_u32_e32 v124, s79, v208
	v_add_u32_e32 v156, s80, v208
	ds_read_b128 v[96:99], v124
	ds_read_b128 v[100:103], v124 offset:1024
	ds_read_b128 v[120:123], v124 offset:2048
	ds_read_b128 v[124:127], v124 offset:3072
	ds_read_b128 v[144:147], v156
	ds_read_b128 v[148:151], v156 offset:1024
	ds_read_b128 v[152:155], v156 offset:2048
	ds_read_b128 v[156:159], v156 offset:3072
	s_add_u32 s50, s50, 0x40000
	s_addc_u32 s51, s51, 0
	s_mov_b32 m0, s63
	v_lshl_add_u64 v[228:229], s[50:51], 0, v[160:161]
	ds_read_b128 v[178:181], v211 offset:32768
	ds_read_b128 v[182:185], v211 offset:33792
	ds_read_b128 v[186:189], v211 offset:34816
	ds_read_b128 v[190:193], v211 offset:35840
	ds_read_b128 v[194:197], v211 offset:36864
	ds_read_b128 v[198:201], v211 offset:37888
	ds_read_b128 v[202:205], v211 offset:38912
	ds_read_b128 v[218:221], v211 offset:39936
	global_load_lds_dwordx4 v[228:229], off
	v_lshl_add_u64 v[228:229], s[50:51], 0, v[164:165]
	s_mov_b32 m0, s64
	s_nop 0
	global_load_lds_dwordx4 v[228:229], off
	s_waitcnt vmcnt(8)
	s_waitcnt lgkmcnt(0)
	s_barrier
	s_setprio 1
	s_waitcnt lgkmcnt(0)
	v_mfma_f32_16x16x32_bf16 v[140:143], v[96:99], v[178:181], v[140:143]
	v_mfma_f32_16x16x32_bf16 v[136:139], v[120:123], v[178:181], v[136:139]
	v_mfma_f32_16x16x32_bf16 v[116:119], v[96:99], v[186:189], v[116:119]
	v_mfma_f32_16x16x32_bf16 v[112:115], v[120:123], v[186:189], v[112:115]
	v_mfma_f32_16x16x32_bf16 v[92:95], v[96:99], v[194:197], v[92:95]
	v_mfma_f32_16x16x32_bf16 v[88:91], v[120:123], v[194:197], v[88:91]
	v_mfma_f32_16x16x32_bf16 v[76:79], v[96:99], v[202:205], v[76:79]
	v_mfma_f32_16x16x32_bf16 v[72:75], v[120:123], v[202:205], v[72:75]
	v_mfma_f32_16x16x32_bf16 v[140:143], v[100:103], v[182:185], v[140:143]
	v_mfma_f32_16x16x32_bf16 v[136:139], v[124:127], v[182:185], v[136:139]
	v_mfma_f32_16x16x32_bf16 v[116:119], v[100:103], v[190:193], v[116:119]
	v_mfma_f32_16x16x32_bf16 v[112:115], v[124:127], v[190:193], v[112:115]
	v_mfma_f32_16x16x32_bf16 v[92:95], v[100:103], v[198:201], v[92:95]
	v_mfma_f32_16x16x32_bf16 v[88:91], v[124:127], v[198:201], v[88:91]
	v_mfma_f32_16x16x32_bf16 v[76:79], v[100:103], v[218:221], v[76:79]
	v_mfma_f32_16x16x32_bf16 v[72:75], v[124:127], v[218:221], v[72:75]
	s_setprio 0
	s_setprio 1
	v_mfma_f32_16x16x32_bf16 v[132:135], v[144:147], v[178:181], v[132:135]
	v_mfma_f32_16x16x32_bf16 v[128:131], v[152:155], v[178:181], v[128:131]
	v_mfma_f32_16x16x32_bf16 v[108:111], v[144:147], v[186:189], v[108:111]
	v_mfma_f32_16x16x32_bf16 v[104:107], v[152:155], v[186:189], v[104:107]
	v_mfma_f32_16x16x32_bf16 v[84:87], v[144:147], v[194:197], v[84:87]
	v_mfma_f32_16x16x32_bf16 v[80:83], v[152:155], v[194:197], v[80:83]
	v_mfma_f32_16x16x32_bf16 v[68:71], v[144:147], v[202:205], v[68:71]
	v_mfma_f32_16x16x32_bf16 v[64:67], v[152:155], v[202:205], v[64:67]
	v_mfma_f32_16x16x32_bf16 v[132:135], v[148:151], v[182:185], v[132:135]
	v_mfma_f32_16x16x32_bf16 v[128:131], v[156:159], v[182:185], v[128:131]
	v_mfma_f32_16x16x32_bf16 v[108:111], v[148:151], v[190:193], v[108:111]
	v_mfma_f32_16x16x32_bf16 v[104:107], v[156:159], v[190:193], v[104:107]
	s_setprio 2
	s_barrier
	v_mfma_f32_16x16x32_bf16 v[84:87], v[148:151], v[198:201], v[84:87]
	v_mfma_f32_16x16x32_bf16 v[80:83], v[156:159], v[198:201], v[80:83]
	v_mfma_f32_16x16x32_bf16 v[68:71], v[148:151], v[218:221], v[68:71]
	v_mfma_f32_16x16x32_bf16 v[64:67], v[156:159], v[218:221], v[64:67]
	s_setprio 0
	s_add_i32 s50, s79, s61
	v_lshl_add_u64 v[206:207], v[206:207], 0, s[36:37]
	s_mov_b32 m0, s50
	ds_read_b128 v[178:181], v211 offset:49152
	ds_read_b128 v[182:185], v211 offset:50176
	ds_read_b128 v[186:189], v211 offset:51200
	ds_read_b128 v[190:193], v211 offset:52224
	ds_read_b128 v[194:197], v211 offset:53248
	ds_read_b128 v[198:201], v211 offset:54272
	ds_read_b128 v[202:205], v211 offset:55296
	ds_read_b128 v[218:221], v211 offset:56320
	global_load_lds_dwordx4 v[206:207], off
	s_add_i32 m0, s50, 0x2000
	s_add_u32 s8, s8, 0x40080
	v_lshl_add_u64 v[206:207], v[222:223], 0, s[36:37]
	s_addc_u32 s9, s9, 0
	s_add_i32 s50, s80, s61
	global_load_lds_dwordx4 v[206:207], off
	v_lshl_add_u64 v[206:207], s[8:9], 0, v[162:163]
	s_mov_b32 m0, s50
	s_nop 0
	global_load_lds_dwordx4 v[206:207], off
	v_lshl_add_u64 v[254:255], s[8:9], 0, v[166:167]
	s_add_i32 s99, s50, 0x2000
	v_lshl_add_u64 v[206:207], v[224:225], 0, s[36:37]
	s_mov_b32 m0, s68
	s_nop 0
	global_load_lds_dwordx4 v[206:207], off
	v_lshl_add_u64 v[206:207], v[226:227], 0, s[36:37]
	s_mov_b32 m0, s69
	s_nop 0
	global_load_lds_dwordx4 v[206:207], off
	s_waitcnt vmcnt(7)
	s_waitcnt lgkmcnt(0)
	s_barrier
	s_setprio 1
	s_waitcnt lgkmcnt(0)
	v_mfma_f32_16x16x32_bf16 v[60:63], v[96:99], v[178:181], v[60:63]
	v_mfma_f32_16x16x32_bf16 v[56:59], v[120:123], v[178:181], v[56:59]
	v_mfma_f32_16x16x32_bf16 v[44:47], v[96:99], v[186:189], v[44:47]
	v_mfma_f32_16x16x32_bf16 v[40:43], v[120:123], v[186:189], v[40:43]
	v_mfma_f32_16x16x32_bf16 v[28:31], v[96:99], v[194:197], v[28:31]
	v_mfma_f32_16x16x32_bf16 v[24:27], v[120:123], v[194:197], v[24:27]
	v_mfma_f32_16x16x32_bf16 v[12:15], v[96:99], v[202:205], v[12:15]
	v_mfma_f32_16x16x32_bf16 v[8:11], v[120:123], v[202:205], v[8:11]
	v_mfma_f32_16x16x32_bf16 v[60:63], v[100:103], v[182:185], v[60:63]
	v_mfma_f32_16x16x32_bf16 v[56:59], v[124:127], v[182:185], v[56:59]
	v_mfma_f32_16x16x32_bf16 v[44:47], v[100:103], v[190:193], v[44:47]
	v_mfma_f32_16x16x32_bf16 v[40:43], v[124:127], v[190:193], v[40:43]
	v_mfma_f32_16x16x32_bf16 v[28:31], v[100:103], v[198:201], v[28:31]
	v_mfma_f32_16x16x32_bf16 v[24:27], v[124:127], v[198:201], v[24:27]
	v_mfma_f32_16x16x32_bf16 v[12:15], v[100:103], v[218:221], v[12:15]
	v_mfma_f32_16x16x32_bf16 v[8:11], v[124:127], v[218:221], v[8:11]
	s_setprio 0
	s_setprio 1
	v_mfma_f32_16x16x32_bf16 v[52:55], v[144:147], v[178:181], v[52:55]
	v_mfma_f32_16x16x32_bf16 v[48:51], v[152:155], v[178:181], v[48:51]
	v_mfma_f32_16x16x32_bf16 v[36:39], v[144:147], v[186:189], v[36:39]
	v_mfma_f32_16x16x32_bf16 v[32:35], v[152:155], v[186:189], v[32:35]
	v_mfma_f32_16x16x32_bf16 v[20:23], v[144:147], v[194:197], v[20:23]
	v_mfma_f32_16x16x32_bf16 v[16:19], v[152:155], v[194:197], v[16:19]
	v_mfma_f32_16x16x32_bf16 v[4:7], v[144:147], v[202:205], v[4:7]
	v_mfma_f32_16x16x32_bf16 v[0:3], v[152:155], v[202:205], v[0:3]
	v_mfma_f32_16x16x32_bf16 v[52:55], v[148:151], v[182:185], v[52:55]
	v_mfma_f32_16x16x32_bf16 v[48:51], v[156:159], v[182:185], v[48:51]
	v_mfma_f32_16x16x32_bf16 v[36:39], v[148:151], v[190:193], v[36:39]
	v_mfma_f32_16x16x32_bf16 v[32:35], v[156:159], v[190:193], v[32:35]
	s_setprio 2
	s_barrier
	v_mfma_f32_16x16x32_bf16 v[20:23], v[148:151], v[198:201], v[20:23]
	v_mfma_f32_16x16x32_bf16 v[16:19], v[156:159], v[198:201], v[16:19]
	v_mfma_f32_16x16x32_bf16 v[4:7], v[148:151], v[218:221], v[4:7]
	v_mfma_f32_16x16x32_bf16 v[0:3], v[156:159], v[218:221], v[0:3]
	s_setprio 0
	s_add_i32 s78, s78, 2
	s_add_u32 s6, s6, 0x100
	s_addc_u32 s7, s7, 0
	s_add_u32 s56, s56, 0x100
	s_addc_u32 s57, s57, 0
	s_cmp_gt_u32 s78, 13
	s_cbranch_scc0 .LBB0_323

.LBB0_778:
	s_add_u32 s12, s4, 0x100000
	s_addc_u32 s13, s5, 0
	s_add_u32 s14, s4, 0x4800000
	s_addc_u32 s15, s5, 0
	s_lshl_b32 s56, s17, 6
	s_lshl_b32 s19, s17, 13
	s_lshl_b32 s4, s16, 5
	s_mov_b64 s[16:17], 0x80
	s_and_b32 s20, s4, 0x60
	s_add_i32 m0, s50, 0x18000
	v_lshl_add_u64 v[6:7], v[6:7], 0, s[16:17]
	s_lshl_b32 s22, s20, 7
	s_waitcnt vmcnt(2)
	s_barrier
	global_load_lds_dwordx4 v[6:7], off
	v_lshl_add_u64 v[4:5], v[4:5], 0, s[16:17]
	s_add_i32 m0, s50, 0x1a000
	s_add_i32 s57, s50, 0x8000
	s_add_i32 s58, s50, 0xa000
	global_load_lds_dwordx4 v[4:5], off
	v_lshl_add_u64 v[0:1], v[0:1], 0, s[16:17]
	s_mov_b32 m0, s57
	s_add_u32 s4, s38, 0x40080
	global_load_lds_dwordx4 v[0:1], off
	v_lshl_add_u64 v[0:1], v[2:3], 0, s[16:17]
	s_mov_b32 m0, s58
	s_addc_u32 s5, s39, 0
	global_load_lds_dwordx4 v[0:1], off
	s_add_i32 m0, s50, 0x1c000
	v_lshl_add_u64 v[0:1], s[4:5], 0, v[132:133]
	global_load_lds_dwordx4 v[0:1], off
	v_lshl_add_u64 v[0:1], s[4:5], 0, v[128:129]
	s_add_i32 m0, s50, 0x1e000
	s_movk_i32 s4, 0x3c0
	global_load_lds_dwordx4 v[0:1], off
	v_mov_b32_e32 v254, v0
	v_mov_b32_e32 v255, v1
	s_add_i32 s99, s50, 0x1e000
	v_and_b32_e32 v0, 48, v8
	v_lshlrev_b32_e32 v1, 6, v8
	v_and_or_b32 v0, v1, s4, v0
	v_lshlrev_b32_e32 v1, 2, v8
	v_and_b32_e32 v1, 32, v1
	v_bitop3_b32 v2, v0, s19, v1 bitop3:0xde
	v_bitop3_b32 v162, s22, v0, v1 bitop3:0xf6
	v_lshlrev_b32_e32 v0, 14, v13
	v_and_b32_e32 v0, 0xffff8000, v0
	v_lshl_add_u32 v0, v12, 11, v0
	v_and_b32_e32 v1, 1, v13
	v_lshl_or_b32 v0, v1, 6, v0
	v_lshl_add_u32 v136, v14, 1, v0
	v_lshlrev_b32_e32 v0, 14, v9
	v_and_b32_e32 v0, 0xffff8000, v0
	s_waitcnt vmcnt(6)
	s_cmpk_lt_u32 s18, 0x100
	v_lshl_add_u32 v0, v10, 11, v0
	v_and_b32_e32 v1, 1, v9
	s_cselect_b64 s[18:19], -1, 0
	v_lshl_or_b32 v0, v1, 6, v0
	s_add_i32 s59, 0, 0x10000
	s_add_i32 s60, 0, 0x14000
	s_sext_i32_i16 s21, s6
	v_mov_b32_e32 v137, v133
	v_lshl_add_u32 v138, v11, 1, v0
	v_mov_b32_e32 v139, v133
	v_mov_b64_e32 v[140:141], 0xb00
	v_mov_b64_e32 v[142:143], 0xaff
	v_add_u32_e32 v163, s59, v162
	v_add_u32_e32 v164, s60, v162
	v_add_u32_e32 v165, 0, v2
	v_mov_b32_e32 v166, 0x358637bd
	s_movk_i32 s61, 0x1600
	s_lshl_b32 s20, s20, 1
	s_mov_b32 s6, s7
	s_barrier
	s_branch .LBB0_781

.LBB0_784:
	s_mov_b32 m0, s99
	s_nop 0
	global_load_lds_dwordx4 v[254:255], off
	ds_read_b128 v[144:147], v163
	ds_read_b128 v[148:151], v163 offset:1024
	ds_read_b128 v[152:155], v163 offset:2048
	ds_read_b128 v[156:159], v163 offset:3072
	ds_read_b128 v[168:171], v164
	ds_read_b128 v[172:175], v164 offset:1024
	ds_read_b128 v[176:179], v164 offset:2048
	ds_read_b128 v[180:183], v164 offset:3072
	s_add_u32 s38, s36, 0xfffc0080
	s_addc_u32 s39, s37, -1
	s_cmp_eq_u32 s65, 12
	s_cselect_b32 s41, s23, s39
	s_cselect_b32 s40, s31, s38
	s_cselect_b32 s39, s25, s64
	s_cselect_b32 s38, s62, s63
	v_lshl_add_u64 v[160:161], s[36:37], 0, v[136:137]
	s_add_i32 m0, s50, 0xc000
	ds_read_b128 v[184:187], v165
	ds_read_b128 v[188:191], v165 offset:1024
	ds_read_b128 v[192:195], v165 offset:2048
	ds_read_b128 v[196:199], v165 offset:3072
	ds_read_b128 v[200:203], v165 offset:4096
	ds_read_b128 v[204:207], v165 offset:5120
	ds_read_b128 v[208:211], v165 offset:6144
	ds_read_b128 v[212:215], v165 offset:7168
	global_load_lds_dwordx4 v[160:161], off
	v_lshl_add_u64 v[160:161], s[36:37], 0, v[138:139]
	s_add_i32 m0, s50, 0xe000
	s_nop 0
	global_load_lds_dwordx4 v[160:161], off
	s_waitcnt vmcnt(8)
	s_waitcnt lgkmcnt(0)
	s_barrier
	s_setprio 1
	s_waitcnt lgkmcnt(0)
	v_mfma_f32_16x16x32_bf16 v[124:127], v[144:147], v[184:187], v[124:127]
	v_mfma_f32_16x16x32_bf16 v[120:123], v[152:155], v[184:187], v[120:123]
	v_mfma_f32_16x16x32_bf16 v[108:111], v[144:147], v[192:195], v[108:111]
	v_mfma_f32_16x16x32_bf16 v[104:107], v[152:155], v[192:195], v[104:107]
	v_mfma_f32_16x16x32_bf16 v[92:95], v[144:147], v[200:203], v[92:95]
	v_mfma_f32_16x16x32_bf16 v[88:91], v[152:155], v[200:203], v[88:91]
	v_mfma_f32_16x16x32_bf16 v[76:79], v[144:147], v[208:211], v[76:79]
	v_mfma_f32_16x16x32_bf16 v[72:75], v[152:155], v[208:211], v[72:75]
	v_mfma_f32_16x16x32_bf16 v[124:127], v[148:151], v[188:191], v[124:127]
	v_mfma_f32_16x16x32_bf16 v[120:123], v[156:159], v[188:191], v[120:123]
	v_mfma_f32_16x16x32_bf16 v[108:111], v[148:151], v[196:199], v[108:111]
	v_mfma_f32_16x16x32_bf16 v[104:107], v[156:159], v[196:199], v[104:107]
	v_mfma_f32_16x16x32_bf16 v[92:95], v[148:151], v[204:207], v[92:95]
	v_mfma_f32_16x16x32_bf16 v[88:91], v[156:159], v[204:207], v[88:91]
	v_mfma_f32_16x16x32_bf16 v[76:79], v[148:151], v[212:215], v[76:79]
	v_mfma_f32_16x16x32_bf16 v[72:75], v[156:159], v[212:215], v[72:75]
	s_setprio 0
	s_setprio 1
	v_mfma_f32_16x16x32_bf16 v[116:119], v[168:171], v[184:187], v[116:119]
	v_mfma_f32_16x16x32_bf16 v[112:115], v[176:179], v[184:187], v[112:115]
	v_mfma_f32_16x16x32_bf16 v[100:103], v[168:171], v[192:195], v[100:103]
	v_mfma_f32_16x16x32_bf16 v[96:99], v[176:179], v[192:195], v[96:99]
	v_mfma_f32_16x16x32_bf16 v[84:87], v[168:171], v[200:203], v[84:87]
	v_mfma_f32_16x16x32_bf16 v[80:83], v[176:179], v[200:203], v[80:83]
	v_mfma_f32_16x16x32_bf16 v[68:71], v[168:171], v[208:211], v[68:71]
	v_mfma_f32_16x16x32_bf16 v[64:67], v[176:179], v[208:211], v[64:67]
	v_mfma_f32_16x16x32_bf16 v[116:119], v[172:175], v[188:191], v[116:119]
	v_mfma_f32_16x16x32_bf16 v[112:115], v[180:183], v[188:191], v[112:115]
	v_mfma_f32_16x16x32_bf16 v[100:103], v[172:175], v[196:199], v[100:103]
	v_mfma_f32_16x16x32_bf16 v[96:99], v[180:183], v[196:199], v[96:99]
	s_setprio 2
	s_barrier
	v_mfma_f32_16x16x32_bf16 v[84:87], v[172:175], v[204:207], v[84:87]
	v_mfma_f32_16x16x32_bf16 v[80:83], v[180:183], v[204:207], v[80:83]
	v_mfma_f32_16x16x32_bf16 v[68:71], v[172:175], v[212:215], v[68:71]
	v_mfma_f32_16x16x32_bf16 v[64:67], v[180:183], v[212:215], v[64:67]
	s_setprio 0
	s_add_i32 s66, s59, s47
	v_lshl_add_u64 v[160:161], s[38:39], 0, v[132:133]
	s_mov_b32 m0, s66
	ds_read_b128 v[184:187], v165 offset:16384
	ds_read_b128 v[188:191], v165 offset:17408
	ds_read_b128 v[192:195], v165 offset:18432
	ds_read_b128 v[196:199], v165 offset:19456
	ds_read_b128 v[200:203], v165 offset:20480
	ds_read_b128 v[204:207], v165 offset:21504
	ds_read_b128 v[208:211], v165 offset:22528
	ds_read_b128 v[212:215], v165 offset:23552
	global_load_lds_dwordx4 v[160:161], off
	s_add_i32 m0, s66, 0x2000
	s_add_u32 s66, s38, 0x40000
	v_lshl_add_u64 v[216:217], s[38:39], 0, v[128:129]
	s_addc_u32 s67, s39, 0
	s_add_i32 s68, s60, s47
	global_load_lds_dwordx4 v[216:217], off
	v_lshl_add_u64 v[218:219], s[66:67], 0, v[132:133]
	s_mov_b32 m0, s68
	v_lshl_add_u64 v[220:221], s[40:41], 0, v[130:131]
	global_load_lds_dwordx4 v[218:219], off
	v_lshl_add_u64 v[218:219], s[40:41], 0, v[134:135]
	s_mov_b32 m0, s50
	s_nop 0
	global_load_lds_dwordx4 v[218:219], off
	s_mov_b32 m0, s51
	s_nop 0
	global_load_lds_dwordx4 v[220:221], off
	s_waitcnt vmcnt(7)
	s_waitcnt lgkmcnt(0)
	s_barrier
	s_setprio 1
	s_waitcnt lgkmcnt(0)
	v_mfma_f32_16x16x32_bf16 v[60:63], v[144:147], v[184:187], v[60:63]
	v_mfma_f32_16x16x32_bf16 v[56:59], v[152:155], v[184:187], v[56:59]
	v_mfma_f32_16x16x32_bf16 v[44:47], v[144:147], v[192:195], v[44:47]
	v_mfma_f32_16x16x32_bf16 v[40:43], v[152:155], v[192:195], v[40:43]
	v_mfma_f32_16x16x32_bf16 v[28:31], v[144:147], v[200:203], v[28:31]
	v_mfma_f32_16x16x32_bf16 v[24:27], v[152:155], v[200:203], v[24:27]
	v_mfma_f32_16x16x32_bf16 v[12:15], v[144:147], v[208:211], v[12:15]
	v_mfma_f32_16x16x32_bf16 v[8:11], v[152:155], v[208:211], v[8:11]
	v_mfma_f32_16x16x32_bf16 v[60:63], v[148:151], v[188:191], v[60:63]
	v_mfma_f32_16x16x32_bf16 v[56:59], v[156:159], v[188:191], v[56:59]
	v_mfma_f32_16x16x32_bf16 v[44:47], v[148:151], v[196:199], v[44:47]
	v_mfma_f32_16x16x32_bf16 v[40:43], v[156:159], v[196:199], v[40:43]
	v_mfma_f32_16x16x32_bf16 v[28:31], v[148:151], v[204:207], v[28:31]
	v_mfma_f32_16x16x32_bf16 v[24:27], v[156:159], v[204:207], v[24:27]
	v_mfma_f32_16x16x32_bf16 v[12:15], v[148:151], v[212:215], v[12:15]
	v_mfma_f32_16x16x32_bf16 v[8:11], v[156:159], v[212:215], v[8:11]
	s_setprio 0
	s_setprio 1
	v_mfma_f32_16x16x32_bf16 v[52:55], v[168:171], v[184:187], v[52:55]
	v_mfma_f32_16x16x32_bf16 v[48:51], v[176:179], v[184:187], v[48:51]
	v_mfma_f32_16x16x32_bf16 v[36:39], v[168:171], v[192:195], v[36:39]
	v_mfma_f32_16x16x32_bf16 v[32:35], v[176:179], v[192:195], v[32:35]
	v_mfma_f32_16x16x32_bf16 v[20:23], v[168:171], v[200:203], v[20:23]
	v_mfma_f32_16x16x32_bf16 v[16:19], v[176:179], v[200:203], v[16:19]
	v_mfma_f32_16x16x32_bf16 v[4:7], v[168:171], v[208:211], v[4:7]
	v_mfma_f32_16x16x32_bf16 v[0:3], v[176:179], v[208:211], v[0:3]
	v_mfma_f32_16x16x32_bf16 v[52:55], v[172:175], v[188:191], v[52:55]
	v_mfma_f32_16x16x32_bf16 v[48:51], v[180:183], v[188:191], v[48:51]
	v_mfma_f32_16x16x32_bf16 v[36:39], v[172:175], v[196:199], v[36:39]
	v_mfma_f32_16x16x32_bf16 v[32:35], v[180:183], v[196:199], v[32:35]
	s_setprio 2
	s_barrier
	v_mfma_f32_16x16x32_bf16 v[20:23], v[172:175], v[204:207], v[20:23]
	v_mfma_f32_16x16x32_bf16 v[16:19], v[180:183], v[204:207], v[16:19]
	v_mfma_f32_16x16x32_bf16 v[4:7], v[172:175], v[212:215], v[4:7]
	v_mfma_f32_16x16x32_bf16 v[0:3], v[180:183], v[212:215], v[0:3]
	s_setprio 0
	v_lshl_add_u64 v[252:253], s[66:67], 0, v[128:129]
	s_add_i32 m0, s68, 0x2000
	s_nop 0
	global_load_lds_dwordx4 v[252:253], off
	s_add_i32 s66, 0, 0x18000
	s_add_i32 s67, 0, 0x1c000
	v_add_u32_e32 v156, s66, v162
	v_add_u32_e32 v167, s67, v162
	ds_read_b128 v[144:147], v156
	ds_read_b128 v[148:151], v156 offset:1024
	ds_read_b128 v[152:155], v156 offset:2048
	ds_read_b128 v[156:159], v156 offset:3072
	ds_read_b128 v[168:171], v167
	ds_read_b128 v[172:175], v167 offset:1024
	ds_read_b128 v[176:179], v167 offset:2048
	ds_read_b128 v[180:183], v167 offset:3072
	s_add_u32 s40, s40, 0x40000
	s_addc_u32 s41, s41, 0
	s_mov_b32 m0, s54
	v_lshl_add_u64 v[222:223], s[40:41], 0, v[134:135]
	ds_read_b128 v[184:187], v165 offset:32768
	ds_read_b128 v[188:191], v165 offset:33792
	ds_read_b128 v[192:195], v165 offset:34816
	ds_read_b128 v[196:199], v165 offset:35840
	ds_read_b128 v[200:203], v165 offset:36864
	ds_read_b128 v[204:207], v165 offset:37888
	ds_read_b128 v[208:211], v165 offset:38912
	ds_read_b128 v[212:215], v165 offset:39936
	global_load_lds_dwordx4 v[222:223], off
	v_lshl_add_u64 v[222:223], s[40:41], 0, v[130:131]
	s_mov_b32 m0, s55
	s_nop 0
	global_load_lds_dwordx4 v[222:223], off
	s_waitcnt vmcnt(8)
	s_waitcnt lgkmcnt(0)
	s_barrier
	s_setprio 1
	s_waitcnt lgkmcnt(0)
	v_mfma_f32_16x16x32_bf16 v[124:127], v[144:147], v[184:187], v[124:127]
	v_mfma_f32_16x16x32_bf16 v[120:123], v[152:155], v[184:187], v[120:123]
	v_mfma_f32_16x16x32_bf16 v[108:111], v[144:147], v[192:195], v[108:111]
	v_mfma_f32_16x16x32_bf16 v[104:107], v[152:155], v[192:195], v[104:107]
	v_mfma_f32_16x16x32_bf16 v[92:95], v[144:147], v[200:203], v[92:95]
	v_mfma_f32_16x16x32_bf16 v[88:91], v[152:155], v[200:203], v[88:91]
	v_mfma_f32_16x16x32_bf16 v[76:79], v[144:147], v[208:211], v[76:79]
	v_mfma_f32_16x16x32_bf16 v[72:75], v[152:155], v[208:211], v[72:75]
	v_mfma_f32_16x16x32_bf16 v[124:127], v[148:151], v[188:191], v[124:127]
	v_mfma_f32_16x16x32_bf16 v[120:123], v[156:159], v[188:191], v[120:123]
	v_mfma_f32_16x16x32_bf16 v[108:111], v[148:151], v[196:199], v[108:111]
	v_mfma_f32_16x16x32_bf16 v[104:107], v[156:159], v[196:199], v[104:107]
	v_mfma_f32_16x16x32_bf16 v[92:95], v[148:151], v[204:207], v[92:95]
	v_mfma_f32_16x16x32_bf16 v[88:91], v[156:159], v[204:207], v[88:91]
	v_mfma_f32_16x16x32_bf16 v[76:79], v[148:151], v[212:215], v[76:79]
	v_mfma_f32_16x16x32_bf16 v[72:75], v[156:159], v[212:215], v[72:75]
	s_setprio 0
	s_setprio 1
	v_mfma_f32_16x16x32_bf16 v[116:119], v[168:171], v[184:187], v[116:119]
	v_mfma_f32_16x16x32_bf16 v[112:115], v[176:179], v[184:187], v[112:115]
	v_mfma_f32_16x16x32_bf16 v[100:103], v[168:171], v[192:195], v[100:103]
	v_mfma_f32_16x16x32_bf16 v[96:99], v[176:179], v[192:195], v[96:99]
	v_mfma_f32_16x16x32_bf16 v[84:87], v[168:171], v[200:203], v[84:87]
	v_mfma_f32_16x16x32_bf16 v[80:83], v[176:179], v[200:203], v[80:83]
	v_mfma_f32_16x16x32_bf16 v[68:71], v[168:171], v[208:211], v[68:71]
	v_mfma_f32_16x16x32_bf16 v[64:67], v[176:179], v[208:211], v[64:67]
	v_mfma_f32_16x16x32_bf16 v[116:119], v[172:175], v[188:191], v[116:119]
	v_mfma_f32_16x16x32_bf16 v[112:115], v[180:183], v[188:191], v[112:115]
	v_mfma_f32_16x16x32_bf16 v[100:103], v[172:175], v[196:199], v[100:103]
	v_mfma_f32_16x16x32_bf16 v[96:99], v[180:183], v[196:199], v[96:99]
	s_setprio 2
	s_barrier
	v_mfma_f32_16x16x32_bf16 v[84:87], v[172:175], v[204:207], v[84:87]
	v_mfma_f32_16x16x32_bf16 v[80:83], v[180:183], v[204:207], v[80:83]
	v_mfma_f32_16x16x32_bf16 v[68:71], v[172:175], v[212:215], v[68:71]
	v_mfma_f32_16x16x32_bf16 v[64:67], v[180:183], v[212:215], v[64:67]
	s_setprio 0
	s_add_i32 s40, s66, s47
	v_lshl_add_u64 v[160:161], v[160:161], 0, s[16:17]
	s_mov_b32 m0, s40
	ds_read_b128 v[184:187], v165 offset:49152
	ds_read_b128 v[188:191], v165 offset:50176
	ds_read_b128 v[192:195], v165 offset:51200
	ds_read_b128 v[196:199], v165 offset:52224
	ds_read_b128 v[200:203], v165 offset:53248
	ds_read_b128 v[204:207], v165 offset:54272
	ds_read_b128 v[208:211], v165 offset:55296
	ds_read_b128 v[212:215], v165 offset:56320
	global_load_lds_dwordx4 v[160:161], off
	s_add_i32 m0, s40, 0x2000
	s_add_u32 s38, s38, 0x40080
	v_lshl_add_u64 v[160:161], v[216:217], 0, s[16:17]
	s_addc_u32 s39, s39, 0
	s_add_i32 s40, s67, s47
	global_load_lds_dwordx4 v[160:161], off
	v_lshl_add_u64 v[160:161], s[38:39], 0, v[132:133]
	s_mov_b32 m0, s40
	s_nop 0
	global_load_lds_dwordx4 v[160:161], off
	v_lshl_add_u64 v[254:255], s[38:39], 0, v[128:129]
	s_add_i32 s99, s40, 0x2000
	v_lshl_add_u64 v[160:161], v[218:219], 0, s[16:17]
	s_mov_b32 m0, s57
	s_nop 0
	global_load_lds_dwordx4 v[160:161], off
	v_lshl_add_u64 v[160:161], v[220:221], 0, s[16:17]
	s_mov_b32 m0, s58
	s_nop 0
	global_load_lds_dwordx4 v[160:161], off
	s_waitcnt vmcnt(7)
	s_waitcnt lgkmcnt(0)
	s_barrier
	s_setprio 1
	s_waitcnt lgkmcnt(0)
	v_mfma_f32_16x16x32_bf16 v[60:63], v[144:147], v[184:187], v[60:63]
	v_mfma_f32_16x16x32_bf16 v[56:59], v[152:155], v[184:187], v[56:59]
	v_mfma_f32_16x16x32_bf16 v[44:47], v[144:147], v[192:195], v[44:47]
	v_mfma_f32_16x16x32_bf16 v[40:43], v[152:155], v[192:195], v[40:43]
	v_mfma_f32_16x16x32_bf16 v[28:31], v[144:147], v[200:203], v[28:31]
	v_mfma_f32_16x16x32_bf16 v[24:27], v[152:155], v[200:203], v[24:27]
	v_mfma_f32_16x16x32_bf16 v[12:15], v[144:147], v[208:211], v[12:15]
	v_mfma_f32_16x16x32_bf16 v[8:11], v[152:155], v[208:211], v[8:11]
	v_mfma_f32_16x16x32_bf16 v[60:63], v[148:151], v[188:191], v[60:63]
	v_mfma_f32_16x16x32_bf16 v[56:59], v[156:159], v[188:191], v[56:59]
	v_mfma_f32_16x16x32_bf16 v[44:47], v[148:151], v[196:199], v[44:47]
	v_mfma_f32_16x16x32_bf16 v[40:43], v[156:159], v[196:199], v[40:43]
	v_mfma_f32_16x16x32_bf16 v[28:31], v[148:151], v[204:207], v[28:31]
	v_mfma_f32_16x16x32_bf16 v[24:27], v[156:159], v[204:207], v[24:27]
	v_mfma_f32_16x16x32_bf16 v[12:15], v[148:151], v[212:215], v[12:15]
	v_mfma_f32_16x16x32_bf16 v[8:11], v[156:159], v[212:215], v[8:11]
	s_setprio 0
	s_setprio 1
	v_mfma_f32_16x16x32_bf16 v[52:55], v[168:171], v[184:187], v[52:55]
	v_mfma_f32_16x16x32_bf16 v[48:51], v[176:179], v[184:187], v[48:51]
	v_mfma_f32_16x16x32_bf16 v[36:39], v[168:171], v[192:195], v[36:39]
	v_mfma_f32_16x16x32_bf16 v[32:35], v[176:179], v[192:195], v[32:35]
	v_mfma_f32_16x16x32_bf16 v[20:23], v[168:171], v[200:203], v[20:23]
	v_mfma_f32_16x16x32_bf16 v[16:19], v[176:179], v[200:203], v[16:19]
	v_mfma_f32_16x16x32_bf16 v[4:7], v[168:171], v[208:211], v[4:7]
	v_mfma_f32_16x16x32_bf16 v[0:3], v[176:179], v[208:211], v[0:3]
	v_mfma_f32_16x16x32_bf16 v[52:55], v[172:175], v[188:191], v[52:55]
	v_mfma_f32_16x16x32_bf16 v[48:51], v[180:183], v[188:191], v[48:51]
	v_mfma_f32_16x16x32_bf16 v[36:39], v[172:175], v[196:199], v[36:39]
	v_mfma_f32_16x16x32_bf16 v[32:35], v[180:183], v[196:199], v[32:35]
	s_setprio 2
	s_barrier
	v_mfma_f32_16x16x32_bf16 v[20:23], v[172:175], v[204:207], v[20:23]
	v_mfma_f32_16x16x32_bf16 v[16:19], v[180:183], v[204:207], v[16:19]
	v_mfma_f32_16x16x32_bf16 v[4:7], v[172:175], v[212:215], v[4:7]
	v_mfma_f32_16x16x32_bf16 v[0:3], v[180:183], v[212:215], v[0:3]
	s_setprio 0
	s_add_i32 s65, s65, 2
	s_add_u32 s36, s36, 0x100
	s_addc_u32 s37, s37, 0
	s_add_u32 s63, s63, 0x100
	s_addc_u32 s64, s64, 0
	s_cmp_gt_u32 s65, 13
	s_cbranch_scc0 .LBB0_784

.LBB0_852:
	s_add_u32 s14, s4, 0x14800000
	s_addc_u32 s15, s5, 0
	s_add_u32 s16, s4, 0x120000
	s_addc_u32 s17, s5, 0
	s_lshl_b32 s7, s7, 5
	s_mov_b64 s[20:21], 0x80
	s_and_b32 s18, s7, 0x60
	s_add_i32 m0, s44, 0x18000
	v_lshl_add_u64 v[6:7], v[6:7], 0, s[20:21]
	s_lshl_b32 s48, s8, 6
	s_lshl_b32 s8, s8, 13
	s_lshl_b32 s7, s18, 7
	s_waitcnt vmcnt(2)
	s_barrier
	global_load_lds_dwordx4 v[6:7], off
	v_lshl_add_u64 v[4:5], v[4:5], 0, s[20:21]
	s_add_i32 m0, s44, 0x1a000
	s_add_i32 s49, s44, 0x8000
	s_add_i32 s50, s44, 0xa000
	global_load_lds_dwordx4 v[4:5], off
	v_lshl_add_u64 v[0:1], v[0:1], 0, s[20:21]
	s_mov_b32 m0, s49
	s_add_u32 s22, s28, 0xb0080
	global_load_lds_dwordx4 v[0:1], off
	v_lshl_add_u64 v[0:1], v[2:3], 0, s[20:21]
	s_mov_b32 m0, s50
	s_addc_u32 s23, s29, 0
	global_load_lds_dwordx4 v[0:1], off
	s_add_i32 m0, s44, 0x1c000
	v_lshl_add_u64 v[0:1], s[22:23], 0, v[186:187]
	global_load_lds_dwordx4 v[0:1], off
	v_lshl_add_u64 v[0:1], s[22:23], 0, v[190:191]
	s_add_i32 m0, s44, 0x1e000
	s_movk_i32 s22, 0x3c0
	global_load_lds_dwordx4 v[0:1], off
	v_mov_b32_e32 v254, v0
	v_mov_b32_e32 v255, v1
	s_add_i32 s99, s44, 0x1e000
	v_and_b32_e32 v0, 48, v8
	v_lshlrev_b32_e32 v1, 6, v8
	v_and_or_b32 v0, v1, s22, v0
	v_lshlrev_b32_e32 v1, 2, v8
	v_and_b32_e32 v1, 32, v1
	s_cmpk_lt_u32 s19, 0x100
	v_bitop3_b32 v232, s7, v0, v1 bitop3:0xf6
	s_cselect_b64 s[22:23], -1, 0
	s_ashr_i32 s51, s38, 31
	s_lshl_b32 s7, s18, 1
	s_add_u32 s4, s4, s7
	s_addc_u32 s5, s5, 0
	v_bitop3_b32 v2, v0, s8, v1 bitop3:0xde
	s_add_u32 s54, s4, 0xf800000
	v_lshrrev_b32_e32 v1, 1, v9
	v_mul_lo_u32 v0, v11, s6
	s_mov_b32 s7, 0xb000
	s_addc_u32 s55, s5, 0
	v_mad_u64_u32 v[0:1], s[4:5], v1, s7, v[0:1]
	v_or_b32_e32 v0, v0, v10
	s_mov_b64 s[24:25], 0xb0080
	v_add_lshl_u32 v0, v0, v12, 1
	v_mov_b32_e32 v1, v187
	v_lshl_add_u64 v[192:193], v[0:1], 0, s[24:25]
	v_lshrrev_b32_e32 v1, 1, v13
	v_mul_lo_u32 v0, v14, s6
	v_mad_u64_u32 v[0:1], s[4:5], v1, s7, v[0:1]
	s_waitcnt vmcnt(6)
	v_or_b32_e32 v0, v0, v15
	v_add_lshl_u32 v0, v0, v16, 1
	v_mov_b32_e32 v1, v187
	s_add_i32 s56, 0, 0x10000
	s_add_i32 s57, 0, 0x14000
	s_mov_b32 s19, s9
	v_lshl_add_u64 v[194:195], v[0:1], 0, s[24:25]
	v_mov_b64_e32 v[196:197], 0x200
	v_mov_b64_e32 v[198:199], 0x1ff
	v_add_u32_e32 v233, s56, v232
	v_add_u32_e32 v234, s57, v232
	v_add_u32_e32 v235, 0, v2
	s_mov_b32 s8, s9
	s_barrier
	s_branch .LBB0_855

.LBB0_866:
	s_mov_b32 m0, s99
	s_nop 0
	global_load_lds_dwordx4 v[254:255], off
	ds_read_b128 v[120:123], v233
	ds_read_b128 v[124:127], v233 offset:1024
	ds_read_b128 v[136:139], v233 offset:2048
	ds_read_b128 v[140:143], v233 offset:3072
	ds_read_b128 v[144:147], v234
	ds_read_b128 v[148:151], v234 offset:1024
	ds_read_b128 v[152:155], v234 offset:2048
	ds_read_b128 v[156:159], v234 offset:3072
	s_add_u32 s28, s26, 0x100
	s_addc_u32 s29, s27, 0
	s_cmp_eq_u32 s64, 40
	s_cselect_b32 s37, s7, s29
	s_cselect_b32 s36, s6, s28
	s_cselect_b32 s31, s25, s63
	s_cselect_b32 s30, s24, s62
	v_lshl_add_u64 v[208:209], s[26:27], 0, v[192:193]
	s_add_i32 m0, s44, 0xc000
	ds_read_b128 v[160:163], v235
	ds_read_b128 v[164:167], v235 offset:1024
	ds_read_b128 v[168:171], v235 offset:2048
	ds_read_b128 v[172:175], v235 offset:3072
	ds_read_b128 v[176:179], v235 offset:4096
	ds_read_b128 v[180:183], v235 offset:5120
	ds_read_b128 v[200:203], v235 offset:6144
	ds_read_b128 v[204:207], v235 offset:7168
	global_load_lds_dwordx4 v[208:209], off
	v_lshl_add_u64 v[208:209], s[26:27], 0, v[194:195]
	s_add_i32 m0, s44, 0xe000
	s_nop 0
	global_load_lds_dwordx4 v[208:209], off
	s_waitcnt vmcnt(8)
	s_waitcnt lgkmcnt(0)
	s_barrier
	s_setprio 1
	s_waitcnt lgkmcnt(0)
	v_mfma_f32_16x16x32_bf16 v[132:135], v[120:123], v[160:163], v[132:135]
	v_mfma_f32_16x16x32_bf16 v[128:131], v[136:139], v[160:163], v[128:131]
	v_mfma_f32_16x16x32_bf16 v[108:111], v[120:123], v[168:171], v[108:111]
	v_mfma_f32_16x16x32_bf16 v[104:107], v[136:139], v[168:171], v[104:107]
	v_mfma_f32_16x16x32_bf16 v[92:95], v[120:123], v[176:179], v[92:95]
	v_mfma_f32_16x16x32_bf16 v[88:91], v[136:139], v[176:179], v[88:91]
	v_mfma_f32_16x16x32_bf16 v[76:79], v[120:123], v[200:203], v[76:79]
	v_mfma_f32_16x16x32_bf16 v[72:75], v[136:139], v[200:203], v[72:75]
	v_mfma_f32_16x16x32_bf16 v[132:135], v[124:127], v[164:167], v[132:135]
	v_mfma_f32_16x16x32_bf16 v[128:131], v[140:143], v[164:167], v[128:131]
	v_mfma_f32_16x16x32_bf16 v[108:111], v[124:127], v[172:175], v[108:111]
	v_mfma_f32_16x16x32_bf16 v[104:107], v[140:143], v[172:175], v[104:107]
	v_mfma_f32_16x16x32_bf16 v[92:95], v[124:127], v[180:183], v[92:95]
	v_mfma_f32_16x16x32_bf16 v[88:91], v[140:143], v[180:183], v[88:91]
	v_mfma_f32_16x16x32_bf16 v[76:79], v[124:127], v[204:207], v[76:79]
	v_mfma_f32_16x16x32_bf16 v[72:75], v[140:143], v[204:207], v[72:75]
	s_setprio 0
	s_setprio 1
	v_mfma_f32_16x16x32_bf16 v[116:119], v[144:147], v[160:163], v[116:119]
	v_mfma_f32_16x16x32_bf16 v[112:115], v[152:155], v[160:163], v[112:115]
	v_mfma_f32_16x16x32_bf16 v[100:103], v[144:147], v[168:171], v[100:103]
	v_mfma_f32_16x16x32_bf16 v[96:99], v[152:155], v[168:171], v[96:99]
	v_mfma_f32_16x16x32_bf16 v[84:87], v[144:147], v[176:179], v[84:87]
	v_mfma_f32_16x16x32_bf16 v[80:83], v[152:155], v[176:179], v[80:83]
	v_mfma_f32_16x16x32_bf16 v[68:71], v[144:147], v[200:203], v[68:71]
	v_mfma_f32_16x16x32_bf16 v[64:67], v[152:155], v[200:203], v[64:67]
	v_mfma_f32_16x16x32_bf16 v[116:119], v[148:151], v[164:167], v[116:119]
	v_mfma_f32_16x16x32_bf16 v[112:115], v[156:159], v[164:167], v[112:115]
	v_mfma_f32_16x16x32_bf16 v[100:103], v[148:151], v[172:175], v[100:103]
	v_mfma_f32_16x16x32_bf16 v[96:99], v[156:159], v[172:175], v[96:99]
	s_setprio 2
	s_barrier
	v_mfma_f32_16x16x32_bf16 v[84:87], v[148:151], v[180:183], v[84:87]
	v_mfma_f32_16x16x32_bf16 v[80:83], v[156:159], v[180:183], v[80:83]
	v_mfma_f32_16x16x32_bf16 v[68:71], v[148:151], v[204:207], v[68:71]
	v_mfma_f32_16x16x32_bf16 v[64:67], v[156:159], v[204:207], v[64:67]
	s_setprio 0
	s_add_i32 s26, s56, s43
	v_lshl_add_u64 v[208:209], s[30:31], 0, v[186:187]
	s_mov_b32 m0, s26
	ds_read_b128 v[160:163], v235 offset:16384
	ds_read_b128 v[164:167], v235 offset:17408
	ds_read_b128 v[168:171], v235 offset:18432
	ds_read_b128 v[172:175], v235 offset:19456
	ds_read_b128 v[176:179], v235 offset:20480
	ds_read_b128 v[180:183], v235 offset:21504
	ds_read_b128 v[200:203], v235 offset:22528
	ds_read_b128 v[204:207], v235 offset:23552
	global_load_lds_dwordx4 v[208:209], off
	s_add_i32 m0, s26, 0x2000
	s_add_u32 s26, s30, 0xb0000
	v_lshl_add_u64 v[210:211], s[30:31], 0, v[190:191]
	s_addc_u32 s27, s31, 0
	s_add_i32 s65, s57, s43
	global_load_lds_dwordx4 v[210:211], off
	v_lshl_add_u64 v[212:213], s[26:27], 0, v[186:187]
	s_mov_b32 m0, s65
	v_lshl_add_u64 v[214:215], s[36:37], 0, v[188:189]
	global_load_lds_dwordx4 v[212:213], off
	v_lshl_add_u64 v[212:213], s[36:37], 0, v[184:185]
	s_mov_b32 m0, s44
	s_nop 0
	global_load_lds_dwordx4 v[212:213], off
	s_mov_b32 m0, s45
	s_nop 0
	global_load_lds_dwordx4 v[214:215], off
	s_waitcnt vmcnt(7)
	s_waitcnt lgkmcnt(0)
	s_barrier
	s_setprio 1
	s_waitcnt lgkmcnt(0)
	v_mfma_f32_16x16x32_bf16 v[60:63], v[120:123], v[160:163], v[60:63]
	v_mfma_f32_16x16x32_bf16 v[56:59], v[136:139], v[160:163], v[56:59]
	v_mfma_f32_16x16x32_bf16 v[44:47], v[120:123], v[168:171], v[44:47]
	v_mfma_f32_16x16x32_bf16 v[40:43], v[136:139], v[168:171], v[40:43]
	v_mfma_f32_16x16x32_bf16 v[28:31], v[120:123], v[176:179], v[28:31]
	v_mfma_f32_16x16x32_bf16 v[24:27], v[136:139], v[176:179], v[24:27]
	v_mfma_f32_16x16x32_bf16 v[12:15], v[120:123], v[200:203], v[12:15]
	v_mfma_f32_16x16x32_bf16 v[8:11], v[136:139], v[200:203], v[8:11]
	v_mfma_f32_16x16x32_bf16 v[60:63], v[124:127], v[164:167], v[60:63]
	v_mfma_f32_16x16x32_bf16 v[56:59], v[140:143], v[164:167], v[56:59]
	v_mfma_f32_16x16x32_bf16 v[44:47], v[124:127], v[172:175], v[44:47]
	v_mfma_f32_16x16x32_bf16 v[40:43], v[140:143], v[172:175], v[40:43]
	v_mfma_f32_16x16x32_bf16 v[28:31], v[124:127], v[180:183], v[28:31]
	v_mfma_f32_16x16x32_bf16 v[24:27], v[140:143], v[180:183], v[24:27]
	v_mfma_f32_16x16x32_bf16 v[12:15], v[124:127], v[204:207], v[12:15]
	v_mfma_f32_16x16x32_bf16 v[8:11], v[140:143], v[204:207], v[8:11]
	s_setprio 0
	s_setprio 1
	v_mfma_f32_16x16x32_bf16 v[52:55], v[144:147], v[160:163], v[52:55]
	v_mfma_f32_16x16x32_bf16 v[48:51], v[152:155], v[160:163], v[48:51]
	v_mfma_f32_16x16x32_bf16 v[36:39], v[144:147], v[168:171], v[36:39]
	v_mfma_f32_16x16x32_bf16 v[32:35], v[152:155], v[168:171], v[32:35]
	v_mfma_f32_16x16x32_bf16 v[20:23], v[144:147], v[176:179], v[20:23]
	v_mfma_f32_16x16x32_bf16 v[16:19], v[152:155], v[176:179], v[16:19]
	v_mfma_f32_16x16x32_bf16 v[4:7], v[144:147], v[200:203], v[4:7]
	v_mfma_f32_16x16x32_bf16 v[0:3], v[152:155], v[200:203], v[0:3]
	v_mfma_f32_16x16x32_bf16 v[52:55], v[148:151], v[164:167], v[52:55]
	v_mfma_f32_16x16x32_bf16 v[48:51], v[156:159], v[164:167], v[48:51]
	v_mfma_f32_16x16x32_bf16 v[36:39], v[148:151], v[172:175], v[36:39]
	v_mfma_f32_16x16x32_bf16 v[32:35], v[156:159], v[172:175], v[32:35]
	s_setprio 2
	s_barrier
	v_mfma_f32_16x16x32_bf16 v[20:23], v[148:151], v[180:183], v[20:23]
	v_mfma_f32_16x16x32_bf16 v[16:19], v[156:159], v[180:183], v[16:19]
	v_mfma_f32_16x16x32_bf16 v[4:7], v[148:151], v[204:207], v[4:7]
	v_mfma_f32_16x16x32_bf16 v[0:3], v[156:159], v[204:207], v[0:3]
	s_setprio 0
	v_lshl_add_u64 v[252:253], s[26:27], 0, v[190:191]
	s_add_i32 m0, s65, 0x2000
	s_nop 0
	global_load_lds_dwordx4 v[252:253], off
	s_add_i32 s65, 0, 0x18000
	s_add_i32 s66, 0, 0x1c000
	v_add_u32_e32 v140, s65, v232
	v_add_u32_e32 v156, s66, v232
	ds_read_b128 v[120:123], v140
	ds_read_b128 v[124:127], v140 offset:1024
	ds_read_b128 v[136:139], v140 offset:2048
	ds_read_b128 v[140:143], v140 offset:3072
	ds_read_b128 v[144:147], v156
	ds_read_b128 v[148:151], v156 offset:1024
	ds_read_b128 v[152:155], v156 offset:2048
	ds_read_b128 v[156:159], v156 offset:3072
	s_add_u32 s26, s36, 0xb0000
	s_addc_u32 s27, s37, 0
	s_mov_b32 m0, s46
	v_lshl_add_u64 v[216:217], s[26:27], 0, v[184:185]
	ds_read_b128 v[160:163], v235 offset:32768
	ds_read_b128 v[164:167], v235 offset:33792
	ds_read_b128 v[168:171], v235 offset:34816
	ds_read_b128 v[172:175], v235 offset:35840
	ds_read_b128 v[176:179], v235 offset:36864
	ds_read_b128 v[180:183], v235 offset:37888
	ds_read_b128 v[200:203], v235 offset:38912
	ds_read_b128 v[204:207], v235 offset:39936
	global_load_lds_dwordx4 v[216:217], off
	v_lshl_add_u64 v[216:217], s[26:27], 0, v[188:189]
	s_mov_b32 m0, s47
	s_nop 0
	global_load_lds_dwordx4 v[216:217], off
	s_waitcnt vmcnt(8)
	s_waitcnt lgkmcnt(0)
	s_barrier
	s_setprio 1
	s_waitcnt lgkmcnt(0)
	v_mfma_f32_16x16x32_bf16 v[132:135], v[120:123], v[160:163], v[132:135]
	v_mfma_f32_16x16x32_bf16 v[128:131], v[136:139], v[160:163], v[128:131]
	v_mfma_f32_16x16x32_bf16 v[108:111], v[120:123], v[168:171], v[108:111]
	v_mfma_f32_16x16x32_bf16 v[104:107], v[136:139], v[168:171], v[104:107]
	v_mfma_f32_16x16x32_bf16 v[92:95], v[120:123], v[176:179], v[92:95]
	v_mfma_f32_16x16x32_bf16 v[88:91], v[136:139], v[176:179], v[88:91]
	v_mfma_f32_16x16x32_bf16 v[76:79], v[120:123], v[200:203], v[76:79]
	v_mfma_f32_16x16x32_bf16 v[72:75], v[136:139], v[200:203], v[72:75]
	v_mfma_f32_16x16x32_bf16 v[132:135], v[124:127], v[164:167], v[132:135]
	v_mfma_f32_16x16x32_bf16 v[128:131], v[140:143], v[164:167], v[128:131]
	v_mfma_f32_16x16x32_bf16 v[108:111], v[124:127], v[172:175], v[108:111]
	v_mfma_f32_16x16x32_bf16 v[104:107], v[140:143], v[172:175], v[104:107]
	v_mfma_f32_16x16x32_bf16 v[92:95], v[124:127], v[180:183], v[92:95]
	v_mfma_f32_16x16x32_bf16 v[88:91], v[140:143], v[180:183], v[88:91]
	v_mfma_f32_16x16x32_bf16 v[76:79], v[124:127], v[204:207], v[76:79]
	v_mfma_f32_16x16x32_bf16 v[72:75], v[140:143], v[204:207], v[72:75]
	s_setprio 0
	s_setprio 1
	v_mfma_f32_16x16x32_bf16 v[116:119], v[144:147], v[160:163], v[116:119]
	v_mfma_f32_16x16x32_bf16 v[112:115], v[152:155], v[160:163], v[112:115]
	v_mfma_f32_16x16x32_bf16 v[100:103], v[144:147], v[168:171], v[100:103]
	v_mfma_f32_16x16x32_bf16 v[96:99], v[152:155], v[168:171], v[96:99]
	v_mfma_f32_16x16x32_bf16 v[84:87], v[144:147], v[176:179], v[84:87]
	v_mfma_f32_16x16x32_bf16 v[80:83], v[152:155], v[176:179], v[80:83]
	v_mfma_f32_16x16x32_bf16 v[68:71], v[144:147], v[200:203], v[68:71]
	v_mfma_f32_16x16x32_bf16 v[64:67], v[152:155], v[200:203], v[64:67]
	v_mfma_f32_16x16x32_bf16 v[116:119], v[148:151], v[164:167], v[116:119]
	v_mfma_f32_16x16x32_bf16 v[112:115], v[156:159], v[164:167], v[112:115]
	v_mfma_f32_16x16x32_bf16 v[100:103], v[148:151], v[172:175], v[100:103]
	v_mfma_f32_16x16x32_bf16 v[96:99], v[156:159], v[172:175], v[96:99]
	s_setprio 2
	s_barrier
	v_mfma_f32_16x16x32_bf16 v[84:87], v[148:151], v[180:183], v[84:87]
	v_mfma_f32_16x16x32_bf16 v[80:83], v[156:159], v[180:183], v[80:83]
	v_mfma_f32_16x16x32_bf16 v[68:71], v[148:151], v[204:207], v[68:71]
	v_mfma_f32_16x16x32_bf16 v[64:67], v[156:159], v[204:207], v[64:67]
	s_setprio 0
	s_add_i32 s26, s65, s43
	v_lshl_add_u64 v[208:209], v[208:209], 0, s[20:21]
	s_mov_b32 m0, s26
	ds_read_b128 v[160:163], v235 offset:49152
	ds_read_b128 v[164:167], v235 offset:50176
	ds_read_b128 v[168:171], v235 offset:51200
	ds_read_b128 v[172:175], v235 offset:52224
	ds_read_b128 v[176:179], v235 offset:53248
	ds_read_b128 v[180:183], v235 offset:54272
	ds_read_b128 v[200:203], v235 offset:55296
	ds_read_b128 v[204:207], v235 offset:56320
	global_load_lds_dwordx4 v[208:209], off
	s_add_i32 m0, s26, 0x2000
	s_add_u32 s26, s30, 0xb0080
	v_lshl_add_u64 v[208:209], v[210:211], 0, s[20:21]
	s_addc_u32 s27, s31, 0
	s_add_i32 s30, s66, s43
	global_load_lds_dwordx4 v[208:209], off
	v_lshl_add_u64 v[208:209], s[26:27], 0, v[186:187]
	s_mov_b32 m0, s30
	s_nop 0
	global_load_lds_dwordx4 v[208:209], off
	v_lshl_add_u64 v[254:255], s[26:27], 0, v[190:191]
	s_add_i32 s99, s30, 0x2000
	v_lshl_add_u64 v[208:209], v[212:213], 0, s[20:21]
	s_mov_b32 m0, s49
	s_nop 0
	global_load_lds_dwordx4 v[208:209], off
	v_lshl_add_u64 v[208:209], v[214:215], 0, s[20:21]
	s_mov_b32 m0, s50
	s_nop 0
	global_load_lds_dwordx4 v[208:209], off
	s_waitcnt vmcnt(7)
	s_waitcnt lgkmcnt(0)
	s_barrier
	s_setprio 1
	s_waitcnt lgkmcnt(0)
	v_mfma_f32_16x16x32_bf16 v[60:63], v[120:123], v[160:163], v[60:63]
	v_mfma_f32_16x16x32_bf16 v[56:59], v[136:139], v[160:163], v[56:59]
	v_mfma_f32_16x16x32_bf16 v[44:47], v[120:123], v[168:171], v[44:47]
	v_mfma_f32_16x16x32_bf16 v[40:43], v[136:139], v[168:171], v[40:43]
	v_mfma_f32_16x16x32_bf16 v[28:31], v[120:123], v[176:179], v[28:31]
	v_mfma_f32_16x16x32_bf16 v[24:27], v[136:139], v[176:179], v[24:27]
	v_mfma_f32_16x16x32_bf16 v[12:15], v[120:123], v[200:203], v[12:15]
	v_mfma_f32_16x16x32_bf16 v[8:11], v[136:139], v[200:203], v[8:11]
	v_mfma_f32_16x16x32_bf16 v[60:63], v[124:127], v[164:167], v[60:63]
	v_mfma_f32_16x16x32_bf16 v[56:59], v[140:143], v[164:167], v[56:59]
	v_mfma_f32_16x16x32_bf16 v[44:47], v[124:127], v[172:175], v[44:47]
	v_mfma_f32_16x16x32_bf16 v[40:43], v[140:143], v[172:175], v[40:43]
	v_mfma_f32_16x16x32_bf16 v[28:31], v[124:127], v[180:183], v[28:31]
	v_mfma_f32_16x16x32_bf16 v[24:27], v[140:143], v[180:183], v[24:27]
	v_mfma_f32_16x16x32_bf16 v[12:15], v[124:127], v[204:207], v[12:15]
	v_mfma_f32_16x16x32_bf16 v[8:11], v[140:143], v[204:207], v[8:11]
	s_setprio 0
	s_setprio 1
	v_mfma_f32_16x16x32_bf16 v[52:55], v[144:147], v[160:163], v[52:55]
	v_mfma_f32_16x16x32_bf16 v[48:51], v[152:155], v[160:163], v[48:51]
	v_mfma_f32_16x16x32_bf16 v[36:39], v[144:147], v[168:171], v[36:39]
	v_mfma_f32_16x16x32_bf16 v[32:35], v[152:155], v[168:171], v[32:35]
	v_mfma_f32_16x16x32_bf16 v[20:23], v[144:147], v[176:179], v[20:23]
	v_mfma_f32_16x16x32_bf16 v[16:19], v[152:155], v[176:179], v[16:19]
	v_mfma_f32_16x16x32_bf16 v[4:7], v[144:147], v[200:203], v[4:7]
	v_mfma_f32_16x16x32_bf16 v[0:3], v[152:155], v[200:203], v[0:3]
	v_mfma_f32_16x16x32_bf16 v[52:55], v[148:151], v[164:167], v[52:55]
	v_mfma_f32_16x16x32_bf16 v[48:51], v[156:159], v[164:167], v[48:51]
	v_mfma_f32_16x16x32_bf16 v[36:39], v[148:151], v[172:175], v[36:39]
	v_mfma_f32_16x16x32_bf16 v[32:35], v[156:159], v[172:175], v[32:35]
	s_setprio 2
	s_barrier
	v_mfma_f32_16x16x32_bf16 v[20:23], v[148:151], v[180:183], v[20:23]
	v_mfma_f32_16x16x32_bf16 v[16:19], v[156:159], v[180:183], v[16:19]
	v_mfma_f32_16x16x32_bf16 v[4:7], v[148:151], v[204:207], v[4:7]
	v_mfma_f32_16x16x32_bf16 v[0:3], v[156:159], v[204:207], v[0:3]
	s_setprio 0
	s_add_i32 s64, s64, 2
	s_add_u32 s62, s62, 0x100
	s_addc_u32 s63, s63, 0
	s_cmp_gt_u32 s64, 41
	s_mov_b64 s[26:27], s[28:29]
	s_cbranch_scc0 .LBB0_866

.LBB0_946:
	s_add_u32 s18, s22, 0x120000
	s_addc_u32 s19, s23, 0
	s_add_u32 s58, s22, 0x4800000
	s_addc_u32 s59, s23, 0
	s_add_u32 s20, s22, 0x8800000
	s_addc_u32 s21, s23, 0
	s_add_u32 s60, s22, 0xc800000
	s_addc_u32 s61, s23, 0
	s_mov_b64 s[22:23], 0x80
	s_and_b32 s26, s24, 3
	s_add_i32 m0, s54, 0x18000
	v_lshl_add_u64 v[6:7], v[6:7], 0, s[22:23]
	s_lshl_b32 s62, s25, 6
	s_lshl_b32 s24, s25, 13
	s_lshl_b32 s63, s26, 5
	s_lshl_b32 s25, s26, 12
	s_waitcnt vmcnt(2)
	s_barrier
	global_load_lds_dwordx4 v[6:7], off
	v_lshl_add_u64 v[4:5], v[4:5], 0, s[22:23]
	s_add_i32 m0, s54, 0x1a000
	s_add_i32 s64, s54, 0x8000
	s_add_i32 s65, s54, 0xa000
	global_load_lds_dwordx4 v[4:5], off
	v_lshl_add_u64 v[0:1], v[0:1], 0, s[22:23]
	s_mov_b32 m0, s64
	s_add_u32 s4, s40, 0x40080
	global_load_lds_dwordx4 v[0:1], off
	v_lshl_add_u64 v[0:1], v[2:3], 0, s[22:23]
	s_mov_b32 m0, s65
	s_addc_u32 s5, s41, 0
	global_load_lds_dwordx4 v[0:1], off
	s_add_i32 m0, s54, 0x1c000
	v_lshl_add_u64 v[0:1], s[4:5], 0, v[130:131]
	global_load_lds_dwordx4 v[0:1], off
	v_lshl_add_u64 v[0:1], s[4:5], 0, v[134:135]
	s_add_i32 m0, s54, 0x1e000
	s_movk_i32 s4, 0x3c0
	global_load_lds_dwordx4 v[0:1], off
	v_mov_b32_e32 v254, v0
	v_mov_b32_e32 v255, v1
	s_add_i32 s99, s54, 0x1e000
	v_and_b32_e32 v0, 48, v8
	v_lshlrev_b32_e32 v1, 6, v8
	v_and_or_b32 v0, v1, s4, v0
	v_lshlrev_b32_e32 v1, 2, v8
	v_and_b32_e32 v1, 32, v1
	v_bitop3_b32 v2, v0, s24, v1 bitop3:0xde
	v_bitop3_b32 v178, s25, v0, v1 bitop3:0xf6
	v_lshlrev_b32_e32 v0, 14, v9
	v_and_b32_e32 v0, 0xffff8000, v0
	v_lshl_add_u32 v0, v10, 11, v0
	v_and_b32_e32 v1, 1, v9
	v_lshl_or_b32 v0, v1, 6, v0
	v_lshl_add_u32 v136, v11, 1, v0
	v_lshlrev_b32_e32 v0, 14, v12
	v_and_b32_e32 v0, 0xffff8000, v0
	s_waitcnt vmcnt(6)
	s_cmpk_lt_u32 s14, 0x100
	v_lshl_add_u32 v0, v13, 11, v0
	v_and_b32_e32 v1, 1, v12
	s_cselect_b64 s[24:25], -1, 0
	v_lshl_or_b32 v0, v1, 6, v0
	s_add_i32 s69, 0, 0x10000
	s_add_i32 s70, 0, 0x14000
	s_lshl_b32 s66, s26, 6
	s_ashr_i32 s67, s46, 31
	v_mov_b32_e32 v137, v131
	v_lshl_add_u32 v138, v14, 1, v0
	v_mov_b32_e32 v139, v131
	v_mov_b64_e32 v[140:141], 0x600
	v_mov_b64_e32 v[142:143], 0x5ff
	s_movk_i32 s68, 0xc1
	v_add_u32_e32 v179, s69, v178
	v_add_u32_e32 v180, s70, v178
	v_add_u32_e32 v181, 0, v2
	v_mov_b32_e32 v182, 0x358637bd
	v_mov_b32_e32 v183, 0x3e38aa3b
	s_mov_b32 s14, s15
	s_barrier
	s_branch .LBB0_949

.LBB0_952:
	s_mov_b32 m0, s99
	s_nop 0
	global_load_lds_dwordx4 v[254:255], off
	ds_read_b128 v[144:147], v179
	ds_read_b128 v[148:151], v179 offset:1024
	ds_read_b128 v[152:155], v179 offset:2048
	ds_read_b128 v[156:159], v179 offset:3072
	ds_read_b128 v[160:163], v180
	ds_read_b128 v[164:167], v180 offset:1024
	ds_read_b128 v[168:171], v180 offset:2048
	ds_read_b128 v[172:175], v180 offset:3072
	s_add_u32 s40, s6, 0xfffc0080
	s_addc_u32 s41, s7, -1
	s_cmp_eq_u32 s73, 12
	s_cselect_b32 s45, s27, s41
	s_cselect_b32 s44, s39, s40
	s_cselect_b32 s41, s29, s72
	s_cselect_b32 s40, s43, s71
	v_lshl_add_u64 v[176:177], s[6:7], 0, v[136:137]
	s_add_i32 m0, s54, 0xc000
	ds_read_b128 v[184:187], v181
	ds_read_b128 v[188:191], v181 offset:1024
	ds_read_b128 v[192:195], v181 offset:2048
	ds_read_b128 v[196:199], v181 offset:3072
	ds_read_b128 v[200:203], v181 offset:4096
	ds_read_b128 v[204:207], v181 offset:5120
	ds_read_b128 v[208:211], v181 offset:6144
	ds_read_b128 v[212:215], v181 offset:7168
	global_load_lds_dwordx4 v[176:177], off
	v_lshl_add_u64 v[176:177], s[6:7], 0, v[138:139]
	s_add_i32 m0, s54, 0xe000
	s_nop 0
	global_load_lds_dwordx4 v[176:177], off
	s_waitcnt vmcnt(8)
	s_waitcnt lgkmcnt(0)
	s_barrier
	s_setprio 1
	s_waitcnt lgkmcnt(0)
	v_mfma_f32_16x16x32_bf16 v[124:127], v[144:147], v[184:187], v[124:127]
	v_mfma_f32_16x16x32_bf16 v[120:123], v[152:155], v[184:187], v[120:123]
	v_mfma_f32_16x16x32_bf16 v[108:111], v[144:147], v[192:195], v[108:111]
	v_mfma_f32_16x16x32_bf16 v[104:107], v[152:155], v[192:195], v[104:107]
	v_mfma_f32_16x16x32_bf16 v[92:95], v[144:147], v[200:203], v[92:95]
	v_mfma_f32_16x16x32_bf16 v[88:91], v[152:155], v[200:203], v[88:91]
	v_mfma_f32_16x16x32_bf16 v[76:79], v[144:147], v[208:211], v[76:79]
	v_mfma_f32_16x16x32_bf16 v[72:75], v[152:155], v[208:211], v[72:75]
	v_mfma_f32_16x16x32_bf16 v[124:127], v[148:151], v[188:191], v[124:127]
	v_mfma_f32_16x16x32_bf16 v[120:123], v[156:159], v[188:191], v[120:123]
	v_mfma_f32_16x16x32_bf16 v[108:111], v[148:151], v[196:199], v[108:111]
	v_mfma_f32_16x16x32_bf16 v[104:107], v[156:159], v[196:199], v[104:107]
	v_mfma_f32_16x16x32_bf16 v[92:95], v[148:151], v[204:207], v[92:95]
	v_mfma_f32_16x16x32_bf16 v[88:91], v[156:159], v[204:207], v[88:91]
	v_mfma_f32_16x16x32_bf16 v[76:79], v[148:151], v[212:215], v[76:79]
	v_mfma_f32_16x16x32_bf16 v[72:75], v[156:159], v[212:215], v[72:75]
	s_setprio 0
	s_setprio 1
	v_mfma_f32_16x16x32_bf16 v[116:119], v[160:163], v[184:187], v[116:119]
	v_mfma_f32_16x16x32_bf16 v[112:115], v[168:171], v[184:187], v[112:115]
	v_mfma_f32_16x16x32_bf16 v[100:103], v[160:163], v[192:195], v[100:103]
	v_mfma_f32_16x16x32_bf16 v[96:99], v[168:171], v[192:195], v[96:99]
	v_mfma_f32_16x16x32_bf16 v[84:87], v[160:163], v[200:203], v[84:87]
	v_mfma_f32_16x16x32_bf16 v[80:83], v[168:171], v[200:203], v[80:83]
	v_mfma_f32_16x16x32_bf16 v[68:71], v[160:163], v[208:211], v[68:71]
	v_mfma_f32_16x16x32_bf16 v[64:67], v[168:171], v[208:211], v[64:67]
	v_mfma_f32_16x16x32_bf16 v[116:119], v[164:167], v[188:191], v[116:119]
	v_mfma_f32_16x16x32_bf16 v[112:115], v[172:175], v[188:191], v[112:115]
	v_mfma_f32_16x16x32_bf16 v[100:103], v[164:167], v[196:199], v[100:103]
	v_mfma_f32_16x16x32_bf16 v[96:99], v[172:175], v[196:199], v[96:99]
	s_setprio 2
	s_barrier
	v_mfma_f32_16x16x32_bf16 v[84:87], v[164:167], v[204:207], v[84:87]
	v_mfma_f32_16x16x32_bf16 v[80:83], v[172:175], v[204:207], v[80:83]
	v_mfma_f32_16x16x32_bf16 v[68:71], v[164:167], v[212:215], v[68:71]
	v_mfma_f32_16x16x32_bf16 v[64:67], v[172:175], v[212:215], v[64:67]
	s_setprio 0
	s_add_i32 s74, s69, s51
	v_lshl_add_u64 v[176:177], s[40:41], 0, v[130:131]
	s_mov_b32 m0, s74
	ds_read_b128 v[184:187], v181 offset:16384
	ds_read_b128 v[188:191], v181 offset:17408
	ds_read_b128 v[192:195], v181 offset:18432
	ds_read_b128 v[196:199], v181 offset:19456
	ds_read_b128 v[200:203], v181 offset:20480
	ds_read_b128 v[204:207], v181 offset:21504
	ds_read_b128 v[208:211], v181 offset:22528
	ds_read_b128 v[212:215], v181 offset:23552
	global_load_lds_dwordx4 v[176:177], off
	s_add_i32 m0, s74, 0x2000
	s_add_u32 s74, s40, 0x40000
	v_lshl_add_u64 v[216:217], s[40:41], 0, v[134:135]
	s_addc_u32 s75, s41, 0
	s_add_i32 s76, s70, s51
	global_load_lds_dwordx4 v[216:217], off
	v_lshl_add_u64 v[218:219], s[74:75], 0, v[130:131]
	s_mov_b32 m0, s76
	v_lshl_add_u64 v[220:221], s[44:45], 0, v[132:133]
	global_load_lds_dwordx4 v[218:219], off
	v_lshl_add_u64 v[218:219], s[44:45], 0, v[128:129]
	s_mov_b32 m0, s54
	s_nop 0
	global_load_lds_dwordx4 v[218:219], off
	s_mov_b32 m0, s55
	s_nop 0
	global_load_lds_dwordx4 v[220:221], off
	s_waitcnt vmcnt(7)
	s_waitcnt lgkmcnt(0)
	s_barrier
	s_setprio 1
	s_waitcnt lgkmcnt(0)
	v_mfma_f32_16x16x32_bf16 v[60:63], v[144:147], v[184:187], v[60:63]
	v_mfma_f32_16x16x32_bf16 v[56:59], v[152:155], v[184:187], v[56:59]
	v_mfma_f32_16x16x32_bf16 v[44:47], v[144:147], v[192:195], v[44:47]
	v_mfma_f32_16x16x32_bf16 v[40:43], v[152:155], v[192:195], v[40:43]
	v_mfma_f32_16x16x32_bf16 v[28:31], v[144:147], v[200:203], v[28:31]
	v_mfma_f32_16x16x32_bf16 v[24:27], v[152:155], v[200:203], v[24:27]
	v_mfma_f32_16x16x32_bf16 v[12:15], v[144:147], v[208:211], v[12:15]
	v_mfma_f32_16x16x32_bf16 v[8:11], v[152:155], v[208:211], v[8:11]
	v_mfma_f32_16x16x32_bf16 v[60:63], v[148:151], v[188:191], v[60:63]
	v_mfma_f32_16x16x32_bf16 v[56:59], v[156:159], v[188:191], v[56:59]
	v_mfma_f32_16x16x32_bf16 v[44:47], v[148:151], v[196:199], v[44:47]
	v_mfma_f32_16x16x32_bf16 v[40:43], v[156:159], v[196:199], v[40:43]
	v_mfma_f32_16x16x32_bf16 v[28:31], v[148:151], v[204:207], v[28:31]
	v_mfma_f32_16x16x32_bf16 v[24:27], v[156:159], v[204:207], v[24:27]
	v_mfma_f32_16x16x32_bf16 v[12:15], v[148:151], v[212:215], v[12:15]
	v_mfma_f32_16x16x32_bf16 v[8:11], v[156:159], v[212:215], v[8:11]
	s_setprio 0
	s_setprio 1
	v_mfma_f32_16x16x32_bf16 v[52:55], v[160:163], v[184:187], v[52:55]
	v_mfma_f32_16x16x32_bf16 v[48:51], v[168:171], v[184:187], v[48:51]
	v_mfma_f32_16x16x32_bf16 v[36:39], v[160:163], v[192:195], v[36:39]
	v_mfma_f32_16x16x32_bf16 v[32:35], v[168:171], v[192:195], v[32:35]
	v_mfma_f32_16x16x32_bf16 v[20:23], v[160:163], v[200:203], v[20:23]
	v_mfma_f32_16x16x32_bf16 v[16:19], v[168:171], v[200:203], v[16:19]
	v_mfma_f32_16x16x32_bf16 v[4:7], v[160:163], v[208:211], v[4:7]
	v_mfma_f32_16x16x32_bf16 v[0:3], v[168:171], v[208:211], v[0:3]
	v_mfma_f32_16x16x32_bf16 v[52:55], v[164:167], v[188:191], v[52:55]
	v_mfma_f32_16x16x32_bf16 v[48:51], v[172:175], v[188:191], v[48:51]
	v_mfma_f32_16x16x32_bf16 v[36:39], v[164:167], v[196:199], v[36:39]
	v_mfma_f32_16x16x32_bf16 v[32:35], v[172:175], v[196:199], v[32:35]
	s_setprio 2
	s_barrier
	v_mfma_f32_16x16x32_bf16 v[20:23], v[164:167], v[204:207], v[20:23]
	v_mfma_f32_16x16x32_bf16 v[16:19], v[172:175], v[204:207], v[16:19]
	v_mfma_f32_16x16x32_bf16 v[4:7], v[164:167], v[212:215], v[4:7]
	v_mfma_f32_16x16x32_bf16 v[0:3], v[172:175], v[212:215], v[0:3]
	s_setprio 0
	v_lshl_add_u64 v[252:253], s[74:75], 0, v[134:135]
	s_add_i32 m0, s76, 0x2000
	s_nop 0
	global_load_lds_dwordx4 v[252:253], off
	s_add_i32 s74, 0, 0x18000
	s_add_i32 s75, 0, 0x1c000
	v_add_u32_e32 v156, s74, v178
	v_add_u32_e32 v172, s75, v178
	ds_read_b128 v[144:147], v156
	ds_read_b128 v[148:151], v156 offset:1024
	ds_read_b128 v[152:155], v156 offset:2048
	ds_read_b128 v[156:159], v156 offset:3072
	ds_read_b128 v[160:163], v172
	ds_read_b128 v[164:167], v172 offset:1024
	ds_read_b128 v[168:171], v172 offset:2048
	ds_read_b128 v[172:175], v172 offset:3072
	s_add_u32 s44, s44, 0x40000
	s_addc_u32 s45, s45, 0
	s_mov_b32 m0, s56
	v_lshl_add_u64 v[222:223], s[44:45], 0, v[128:129]
	ds_read_b128 v[184:187], v181 offset:32768
	ds_read_b128 v[188:191], v181 offset:33792
	ds_read_b128 v[192:195], v181 offset:34816
	ds_read_b128 v[196:199], v181 offset:35840
	ds_read_b128 v[200:203], v181 offset:36864
	ds_read_b128 v[204:207], v181 offset:37888
	ds_read_b128 v[208:211], v181 offset:38912
	ds_read_b128 v[212:215], v181 offset:39936
	global_load_lds_dwordx4 v[222:223], off
	v_lshl_add_u64 v[222:223], s[44:45], 0, v[132:133]
	s_mov_b32 m0, s57
	s_nop 0
	global_load_lds_dwordx4 v[222:223], off
	s_waitcnt vmcnt(8)
	s_waitcnt lgkmcnt(0)
	s_barrier
	s_setprio 1
	s_waitcnt lgkmcnt(0)
	v_mfma_f32_16x16x32_bf16 v[124:127], v[144:147], v[184:187], v[124:127]
	v_mfma_f32_16x16x32_bf16 v[120:123], v[152:155], v[184:187], v[120:123]
	v_mfma_f32_16x16x32_bf16 v[108:111], v[144:147], v[192:195], v[108:111]
	v_mfma_f32_16x16x32_bf16 v[104:107], v[152:155], v[192:195], v[104:107]
	v_mfma_f32_16x16x32_bf16 v[92:95], v[144:147], v[200:203], v[92:95]
	v_mfma_f32_16x16x32_bf16 v[88:91], v[152:155], v[200:203], v[88:91]
	v_mfma_f32_16x16x32_bf16 v[76:79], v[144:147], v[208:211], v[76:79]
	v_mfma_f32_16x16x32_bf16 v[72:75], v[152:155], v[208:211], v[72:75]
	v_mfma_f32_16x16x32_bf16 v[124:127], v[148:151], v[188:191], v[124:127]
	v_mfma_f32_16x16x32_bf16 v[120:123], v[156:159], v[188:191], v[120:123]
	v_mfma_f32_16x16x32_bf16 v[108:111], v[148:151], v[196:199], v[108:111]
	v_mfma_f32_16x16x32_bf16 v[104:107], v[156:159], v[196:199], v[104:107]
	v_mfma_f32_16x16x32_bf16 v[92:95], v[148:151], v[204:207], v[92:95]
	v_mfma_f32_16x16x32_bf16 v[88:91], v[156:159], v[204:207], v[88:91]
	v_mfma_f32_16x16x32_bf16 v[76:79], v[148:151], v[212:215], v[76:79]
	v_mfma_f32_16x16x32_bf16 v[72:75], v[156:159], v[212:215], v[72:75]
	s_setprio 0
	s_setprio 1
	v_mfma_f32_16x16x32_bf16 v[116:119], v[160:163], v[184:187], v[116:119]
	v_mfma_f32_16x16x32_bf16 v[112:115], v[168:171], v[184:187], v[112:115]
	v_mfma_f32_16x16x32_bf16 v[100:103], v[160:163], v[192:195], v[100:103]
	v_mfma_f32_16x16x32_bf16 v[96:99], v[168:171], v[192:195], v[96:99]
	v_mfma_f32_16x16x32_bf16 v[84:87], v[160:163], v[200:203], v[84:87]
	v_mfma_f32_16x16x32_bf16 v[80:83], v[168:171], v[200:203], v[80:83]
	v_mfma_f32_16x16x32_bf16 v[68:71], v[160:163], v[208:211], v[68:71]
	v_mfma_f32_16x16x32_bf16 v[64:67], v[168:171], v[208:211], v[64:67]
	v_mfma_f32_16x16x32_bf16 v[116:119], v[164:167], v[188:191], v[116:119]
	v_mfma_f32_16x16x32_bf16 v[112:115], v[172:175], v[188:191], v[112:115]
	v_mfma_f32_16x16x32_bf16 v[100:103], v[164:167], v[196:199], v[100:103]
	v_mfma_f32_16x16x32_bf16 v[96:99], v[172:175], v[196:199], v[96:99]
	s_setprio 2
	s_barrier
	v_mfma_f32_16x16x32_bf16 v[84:87], v[164:167], v[204:207], v[84:87]
	v_mfma_f32_16x16x32_bf16 v[80:83], v[172:175], v[204:207], v[80:83]
	v_mfma_f32_16x16x32_bf16 v[68:71], v[164:167], v[212:215], v[68:71]
	v_mfma_f32_16x16x32_bf16 v[64:67], v[172:175], v[212:215], v[64:67]
	s_setprio 0
	s_add_i32 s44, s74, s51
	v_lshl_add_u64 v[176:177], v[176:177], 0, s[22:23]
	s_mov_b32 m0, s44
	ds_read_b128 v[184:187], v181 offset:49152
	ds_read_b128 v[188:191], v181 offset:50176
	ds_read_b128 v[192:195], v181 offset:51200
	ds_read_b128 v[196:199], v181 offset:52224
	ds_read_b128 v[200:203], v181 offset:53248
	ds_read_b128 v[204:207], v181 offset:54272
	ds_read_b128 v[208:211], v181 offset:55296
	ds_read_b128 v[212:215], v181 offset:56320
	global_load_lds_dwordx4 v[176:177], off
	s_add_i32 m0, s44, 0x2000
	s_add_u32 s40, s40, 0x40080
	v_lshl_add_u64 v[176:177], v[216:217], 0, s[22:23]
	s_addc_u32 s41, s41, 0
	s_add_i32 s44, s75, s51
	global_load_lds_dwordx4 v[176:177], off
	v_lshl_add_u64 v[176:177], s[40:41], 0, v[130:131]
	s_mov_b32 m0, s44
	s_nop 0
	global_load_lds_dwordx4 v[176:177], off
	v_lshl_add_u64 v[254:255], s[40:41], 0, v[134:135]
	s_add_i32 s99, s44, 0x2000
	v_lshl_add_u64 v[176:177], v[218:219], 0, s[22:23]
	s_mov_b32 m0, s64
	s_nop 0
	global_load_lds_dwordx4 v[176:177], off
	v_lshl_add_u64 v[176:177], v[220:221], 0, s[22:23]
	s_mov_b32 m0, s65
	s_nop 0
	global_load_lds_dwordx4 v[176:177], off
	s_waitcnt vmcnt(7)
	s_waitcnt lgkmcnt(0)
	s_barrier
	s_setprio 1
	s_waitcnt lgkmcnt(0)
	v_mfma_f32_16x16x32_bf16 v[60:63], v[144:147], v[184:187], v[60:63]
	v_mfma_f32_16x16x32_bf16 v[56:59], v[152:155], v[184:187], v[56:59]
	v_mfma_f32_16x16x32_bf16 v[44:47], v[144:147], v[192:195], v[44:47]
	v_mfma_f32_16x16x32_bf16 v[40:43], v[152:155], v[192:195], v[40:43]
	v_mfma_f32_16x16x32_bf16 v[28:31], v[144:147], v[200:203], v[28:31]
	v_mfma_f32_16x16x32_bf16 v[24:27], v[152:155], v[200:203], v[24:27]
	v_mfma_f32_16x16x32_bf16 v[12:15], v[144:147], v[208:211], v[12:15]
	v_mfma_f32_16x16x32_bf16 v[8:11], v[152:155], v[208:211], v[8:11]
	v_mfma_f32_16x16x32_bf16 v[60:63], v[148:151], v[188:191], v[60:63]
	v_mfma_f32_16x16x32_bf16 v[56:59], v[156:159], v[188:191], v[56:59]
	v_mfma_f32_16x16x32_bf16 v[44:47], v[148:151], v[196:199], v[44:47]
	v_mfma_f32_16x16x32_bf16 v[40:43], v[156:159], v[196:199], v[40:43]
	v_mfma_f32_16x16x32_bf16 v[28:31], v[148:151], v[204:207], v[28:31]
	v_mfma_f32_16x16x32_bf16 v[24:27], v[156:159], v[204:207], v[24:27]
	v_mfma_f32_16x16x32_bf16 v[12:15], v[148:151], v[212:215], v[12:15]
	v_mfma_f32_16x16x32_bf16 v[8:11], v[156:159], v[212:215], v[8:11]
	s_setprio 0
	s_setprio 1
	v_mfma_f32_16x16x32_bf16 v[52:55], v[160:163], v[184:187], v[52:55]
	v_mfma_f32_16x16x32_bf16 v[48:51], v[168:171], v[184:187], v[48:51]
	v_mfma_f32_16x16x32_bf16 v[36:39], v[160:163], v[192:195], v[36:39]
	v_mfma_f32_16x16x32_bf16 v[32:35], v[168:171], v[192:195], v[32:35]
	v_mfma_f32_16x16x32_bf16 v[20:23], v[160:163], v[200:203], v[20:23]
	v_mfma_f32_16x16x32_bf16 v[16:19], v[168:171], v[200:203], v[16:19]
	v_mfma_f32_16x16x32_bf16 v[4:7], v[160:163], v[208:211], v[4:7]
	v_mfma_f32_16x16x32_bf16 v[0:3], v[168:171], v[208:211], v[0:3]
	v_mfma_f32_16x16x32_bf16 v[52:55], v[164:167], v[188:191], v[52:55]
	v_mfma_f32_16x16x32_bf16 v[48:51], v[172:175], v[188:191], v[48:51]
	v_mfma_f32_16x16x32_bf16 v[36:39], v[164:167], v[196:199], v[36:39]
	v_mfma_f32_16x16x32_bf16 v[32:35], v[172:175], v[196:199], v[32:35]
	s_setprio 2
	s_barrier
	v_mfma_f32_16x16x32_bf16 v[20:23], v[164:167], v[204:207], v[20:23]
	v_mfma_f32_16x16x32_bf16 v[16:19], v[172:175], v[204:207], v[16:19]
	v_mfma_f32_16x16x32_bf16 v[4:7], v[164:167], v[212:215], v[4:7]
	v_mfma_f32_16x16x32_bf16 v[0:3], v[172:175], v[212:215], v[0:3]
	s_setprio 0
	s_add_i32 s73, s73, 2
	s_add_u32 s6, s6, 0x100
	s_addc_u32 s7, s7, 0
	s_add_u32 s71, s71, 0x100
	s_addc_u32 s72, s72, 0
	s_cmp_gt_u32 s73, 13
	s_cbranch_scc0 .LBB0_952

.LBB0_1136:
	s_add_u32 s12, s4, 0x14800000
	s_addc_u32 s13, s5, 0
	s_add_u32 s14, s4, 0x140000
	s_addc_u32 s15, s5, 0
	s_lshl_b32 s4, s6, 5
	s_mov_b64 s[18:19], 0x80
	s_lshl_b32 s56, s16, 6
	s_lshl_b32 s20, s16, 13
	s_and_b32 s16, s4, 0x60
	s_add_i32 m0, s50, 0x18000
	v_lshl_add_u64 v[6:7], v[6:7], 0, s[18:19]
	s_lshl_b32 s6, s16, 7
	s_waitcnt vmcnt(2)
	s_barrier
	global_load_lds_dwordx4 v[6:7], off
	v_lshl_add_u64 v[4:5], v[4:5], 0, s[18:19]
	s_add_i32 m0, s50, 0x1a000
	s_add_i32 s57, s50, 0x8000
	s_add_i32 s58, s50, 0xa000
	global_load_lds_dwordx4 v[4:5], off
	v_lshl_add_u64 v[0:1], v[0:1], 0, s[18:19]
	s_mov_b32 m0, s57
	s_add_u32 s4, s40, 0x40080
	global_load_lds_dwordx4 v[0:1], off
	v_lshl_add_u64 v[0:1], v[2:3], 0, s[18:19]
	s_mov_b32 m0, s58
	s_addc_u32 s5, s41, 0
	global_load_lds_dwordx4 v[0:1], off
	s_add_i32 m0, s50, 0x1c000
	v_lshl_add_u64 v[0:1], s[4:5], 0, v[186:187]
	global_load_lds_dwordx4 v[0:1], off
	v_lshl_add_u64 v[0:1], s[4:5], 0, v[190:191]
	s_add_i32 m0, s50, 0x1e000
	s_movk_i32 s4, 0x3c0
	global_load_lds_dwordx4 v[0:1], off
	v_mov_b32_e32 v254, v0
	v_mov_b32_e32 v255, v1
	s_add_i32 s99, s50, 0x1e000
	v_and_b32_e32 v0, 48, v8
	v_lshlrev_b32_e32 v1, 6, v8
	v_and_or_b32 v0, v1, s4, v0
	v_lshlrev_b32_e32 v1, 2, v8
	v_and_b32_e32 v1, 32, v1
	v_bitop3_b32 v2, v0, s20, v1 bitop3:0xde
	v_bitop3_b32 v232, s6, v0, v1 bitop3:0xf6
	v_lshlrev_b32_e32 v0, 14, v9
	v_and_b32_e32 v0, 0xffff8000, v0
	v_lshl_add_u32 v0, v10, 11, v0
	v_and_b32_e32 v1, 1, v9
	v_lshl_or_b32 v0, v1, 6, v0
	s_cmpk_lt_u32 s17, 0x100
	v_lshl_add_u32 v192, v11, 1, v0
	v_lshlrev_b32_e32 v0, 14, v12
	s_cselect_b64 s[20:21], -1, 0
	s_ashr_i32 s59, s44, 31
	s_lshl_b32 s4, s16, 1
	v_and_b32_e32 v0, 0xffff8000, v0
	s_waitcnt vmcnt(6)
	s_add_u32 s60, s12, s4
	v_lshl_add_u32 v0, v13, 11, v0
	v_and_b32_e32 v1, 1, v12
	s_addc_u32 s61, s13, 0
	v_lshl_or_b32 v0, v1, 6, v0
	s_add_i32 s62, 0, 0x10000
	s_add_i32 s63, 0, 0x14000
	s_mov_b32 s17, s7
	v_mov_b32_e32 v193, v187
	v_lshl_add_u32 v194, v14, 1, v0
	v_mov_b32_e32 v195, v187
	v_mov_b64_e32 v[196:197], 0x200
	v_mov_b64_e32 v[198:199], 0x1ff
	v_add_u32_e32 v233, s62, v232
	v_add_u32_e32 v234, s63, v232
	v_add_u32_e32 v235, 0, v2
	s_mov_b32 s6, s7
	s_barrier
	s_branch .LBB0_1139

.LBB0_1146:
	s_mov_b32 m0, s99
	s_nop 0
	global_load_lds_dwordx4 v[254:255], off
	ds_read_b128 v[120:123], v233
	ds_read_b128 v[132:135], v233 offset:1024
	ds_read_b128 v[136:139], v233 offset:2048
	ds_read_b128 v[140:143], v233 offset:3072
	ds_read_b128 v[144:147], v234
	ds_read_b128 v[148:151], v234 offset:1024
	ds_read_b128 v[152:155], v234 offset:2048
	ds_read_b128 v[156:159], v234 offset:3072
	s_add_u32 s40, s38, 0xfffc0080
	s_addc_u32 s41, s39, -1
	s_cmp_eq_u32 s66, 12
	s_cselect_b32 s43, s23, s41
	s_cselect_b32 s42, s31, s40
	s_cselect_b32 s41, s25, s65
	s_cselect_b32 s40, s37, s64
	v_lshl_add_u64 v[208:209], s[38:39], 0, v[192:193]
	s_add_i32 m0, s50, 0xc000
	ds_read_b128 v[160:163], v235
	ds_read_b128 v[164:167], v235 offset:1024
	ds_read_b128 v[168:171], v235 offset:2048
	ds_read_b128 v[172:175], v235 offset:3072
	ds_read_b128 v[176:179], v235 offset:4096
	ds_read_b128 v[180:183], v235 offset:5120
	ds_read_b128 v[200:203], v235 offset:6144
	ds_read_b128 v[204:207], v235 offset:7168
	global_load_lds_dwordx4 v[208:209], off
	v_lshl_add_u64 v[208:209], s[38:39], 0, v[194:195]
	s_add_i32 m0, s50, 0xe000
	s_nop 0
	global_load_lds_dwordx4 v[208:209], off
	s_waitcnt vmcnt(8)
	s_waitcnt lgkmcnt(0)
	s_barrier
	s_setprio 1
	s_waitcnt lgkmcnt(0)
	v_mfma_f32_16x16x32_bf16 v[128:131], v[120:123], v[160:163], v[128:131]
	v_mfma_f32_16x16x32_bf16 v[124:127], v[136:139], v[160:163], v[124:127]
	v_mfma_f32_16x16x32_bf16 v[108:111], v[120:123], v[168:171], v[108:111]
	v_mfma_f32_16x16x32_bf16 v[104:107], v[136:139], v[168:171], v[104:107]
	v_mfma_f32_16x16x32_bf16 v[92:95], v[120:123], v[176:179], v[92:95]
	v_mfma_f32_16x16x32_bf16 v[88:91], v[136:139], v[176:179], v[88:91]
	v_mfma_f32_16x16x32_bf16 v[76:79], v[120:123], v[200:203], v[76:79]
	v_mfma_f32_16x16x32_bf16 v[72:75], v[136:139], v[200:203], v[72:75]
	v_mfma_f32_16x16x32_bf16 v[128:131], v[132:135], v[164:167], v[128:131]
	v_mfma_f32_16x16x32_bf16 v[124:127], v[140:143], v[164:167], v[124:127]
	v_mfma_f32_16x16x32_bf16 v[108:111], v[132:135], v[172:175], v[108:111]
	v_mfma_f32_16x16x32_bf16 v[104:107], v[140:143], v[172:175], v[104:107]
	v_mfma_f32_16x16x32_bf16 v[92:95], v[132:135], v[180:183], v[92:95]
	v_mfma_f32_16x16x32_bf16 v[88:91], v[140:143], v[180:183], v[88:91]
	v_mfma_f32_16x16x32_bf16 v[76:79], v[132:135], v[204:207], v[76:79]
	v_mfma_f32_16x16x32_bf16 v[72:75], v[140:143], v[204:207], v[72:75]
	s_setprio 0
	s_setprio 1
	v_mfma_f32_16x16x32_bf16 v[116:119], v[144:147], v[160:163], v[116:119]
	v_mfma_f32_16x16x32_bf16 v[112:115], v[152:155], v[160:163], v[112:115]
	v_mfma_f32_16x16x32_bf16 v[100:103], v[144:147], v[168:171], v[100:103]
	v_mfma_f32_16x16x32_bf16 v[96:99], v[152:155], v[168:171], v[96:99]
	v_mfma_f32_16x16x32_bf16 v[84:87], v[144:147], v[176:179], v[84:87]
	v_mfma_f32_16x16x32_bf16 v[80:83], v[152:155], v[176:179], v[80:83]
	v_mfma_f32_16x16x32_bf16 v[68:71], v[144:147], v[200:203], v[68:71]
	v_mfma_f32_16x16x32_bf16 v[64:67], v[152:155], v[200:203], v[64:67]
	v_mfma_f32_16x16x32_bf16 v[116:119], v[148:151], v[164:167], v[116:119]
	v_mfma_f32_16x16x32_bf16 v[112:115], v[156:159], v[164:167], v[112:115]
	v_mfma_f32_16x16x32_bf16 v[100:103], v[148:151], v[172:175], v[100:103]
	v_mfma_f32_16x16x32_bf16 v[96:99], v[156:159], v[172:175], v[96:99]
	s_setprio 2
	s_barrier
	v_mfma_f32_16x16x32_bf16 v[84:87], v[148:151], v[180:183], v[84:87]
	v_mfma_f32_16x16x32_bf16 v[80:83], v[156:159], v[180:183], v[80:83]
	v_mfma_f32_16x16x32_bf16 v[68:71], v[148:151], v[204:207], v[68:71]
	v_mfma_f32_16x16x32_bf16 v[64:67], v[156:159], v[204:207], v[64:67]
	s_setprio 0
	s_add_i32 s67, s62, s49
	v_lshl_add_u64 v[208:209], s[40:41], 0, v[186:187]
	s_mov_b32 m0, s67
	ds_read_b128 v[160:163], v235 offset:16384
	ds_read_b128 v[164:167], v235 offset:17408
	ds_read_b128 v[168:171], v235 offset:18432
	ds_read_b128 v[172:175], v235 offset:19456
	ds_read_b128 v[176:179], v235 offset:20480
	ds_read_b128 v[180:183], v235 offset:21504
	ds_read_b128 v[200:203], v235 offset:22528
	ds_read_b128 v[204:207], v235 offset:23552
	global_load_lds_dwordx4 v[208:209], off
	s_add_i32 m0, s67, 0x2000
	s_add_u32 s68, s40, 0x40000
	v_lshl_add_u64 v[210:211], s[40:41], 0, v[190:191]
	s_addc_u32 s69, s41, 0
	s_add_i32 s67, s63, s49
	global_load_lds_dwordx4 v[210:211], off
	v_lshl_add_u64 v[212:213], s[68:69], 0, v[186:187]
	s_mov_b32 m0, s67
	v_lshl_add_u64 v[214:215], s[42:43], 0, v[188:189]
	global_load_lds_dwordx4 v[212:213], off
	v_lshl_add_u64 v[212:213], s[42:43], 0, v[184:185]
	s_mov_b32 m0, s50
	s_nop 0
	global_load_lds_dwordx4 v[212:213], off
	s_mov_b32 m0, s51
	s_nop 0
	global_load_lds_dwordx4 v[214:215], off
	s_waitcnt vmcnt(7)
	s_waitcnt lgkmcnt(0)
	s_barrier
	s_setprio 1
	s_waitcnt lgkmcnt(0)
	v_mfma_f32_16x16x32_bf16 v[60:63], v[120:123], v[160:163], v[60:63]
	v_mfma_f32_16x16x32_bf16 v[56:59], v[136:139], v[160:163], v[56:59]
	v_mfma_f32_16x16x32_bf16 v[44:47], v[120:123], v[168:171], v[44:47]
	v_mfma_f32_16x16x32_bf16 v[40:43], v[136:139], v[168:171], v[40:43]
	v_mfma_f32_16x16x32_bf16 v[28:31], v[120:123], v[176:179], v[28:31]
	v_mfma_f32_16x16x32_bf16 v[24:27], v[136:139], v[176:179], v[24:27]
	v_mfma_f32_16x16x32_bf16 v[12:15], v[120:123], v[200:203], v[12:15]
	v_mfma_f32_16x16x32_bf16 v[8:11], v[136:139], v[200:203], v[8:11]
	v_mfma_f32_16x16x32_bf16 v[60:63], v[132:135], v[164:167], v[60:63]
	v_mfma_f32_16x16x32_bf16 v[56:59], v[140:143], v[164:167], v[56:59]
	v_mfma_f32_16x16x32_bf16 v[44:47], v[132:135], v[172:175], v[44:47]
	v_mfma_f32_16x16x32_bf16 v[40:43], v[140:143], v[172:175], v[40:43]
	v_mfma_f32_16x16x32_bf16 v[28:31], v[132:135], v[180:183], v[28:31]
	v_mfma_f32_16x16x32_bf16 v[24:27], v[140:143], v[180:183], v[24:27]
	v_mfma_f32_16x16x32_bf16 v[12:15], v[132:135], v[204:207], v[12:15]
	v_mfma_f32_16x16x32_bf16 v[8:11], v[140:143], v[204:207], v[8:11]
	s_setprio 0
	s_setprio 1
	v_mfma_f32_16x16x32_bf16 v[52:55], v[144:147], v[160:163], v[52:55]
	v_mfma_f32_16x16x32_bf16 v[48:51], v[152:155], v[160:163], v[48:51]
	v_mfma_f32_16x16x32_bf16 v[36:39], v[144:147], v[168:171], v[36:39]
	v_mfma_f32_16x16x32_bf16 v[32:35], v[152:155], v[168:171], v[32:35]
	v_mfma_f32_16x16x32_bf16 v[20:23], v[144:147], v[176:179], v[20:23]
	v_mfma_f32_16x16x32_bf16 v[16:19], v[152:155], v[176:179], v[16:19]
	v_mfma_f32_16x16x32_bf16 v[4:7], v[144:147], v[200:203], v[4:7]
	v_mfma_f32_16x16x32_bf16 v[0:3], v[152:155], v[200:203], v[0:3]
	v_mfma_f32_16x16x32_bf16 v[52:55], v[148:151], v[164:167], v[52:55]
	v_mfma_f32_16x16x32_bf16 v[48:51], v[156:159], v[164:167], v[48:51]
	v_mfma_f32_16x16x32_bf16 v[36:39], v[148:151], v[172:175], v[36:39]
	v_mfma_f32_16x16x32_bf16 v[32:35], v[156:159], v[172:175], v[32:35]
	s_setprio 2
	s_barrier
	v_mfma_f32_16x16x32_bf16 v[20:23], v[148:151], v[180:183], v[20:23]
	v_mfma_f32_16x16x32_bf16 v[16:19], v[156:159], v[180:183], v[16:19]
	v_mfma_f32_16x16x32_bf16 v[4:7], v[148:151], v[204:207], v[4:7]
	v_mfma_f32_16x16x32_bf16 v[0:3], v[156:159], v[204:207], v[0:3]
	s_setprio 0
	v_lshl_add_u64 v[252:253], s[68:69], 0, v[190:191]
	s_add_i32 m0, s67, 0x2000
	s_nop 0
	global_load_lds_dwordx4 v[252:253], off
	s_add_i32 s67, 0, 0x18000
	s_add_i32 s68, 0, 0x1c000
	v_add_u32_e32 v140, s67, v232
	v_add_u32_e32 v156, s68, v232
	ds_read_b128 v[120:123], v140
	ds_read_b128 v[132:135], v140 offset:1024
	ds_read_b128 v[136:139], v140 offset:2048
	ds_read_b128 v[140:143], v140 offset:3072
	ds_read_b128 v[144:147], v156
	ds_read_b128 v[148:151], v156 offset:1024
	ds_read_b128 v[152:155], v156 offset:2048
	ds_read_b128 v[156:159], v156 offset:3072
	s_add_u32 s42, s42, 0x40000
	s_addc_u32 s43, s43, 0
	s_mov_b32 m0, s54
	v_lshl_add_u64 v[216:217], s[42:43], 0, v[184:185]
	ds_read_b128 v[160:163], v235 offset:32768
	ds_read_b128 v[164:167], v235 offset:33792
	ds_read_b128 v[168:171], v235 offset:34816
	ds_read_b128 v[172:175], v235 offset:35840
	ds_read_b128 v[176:179], v235 offset:36864
	ds_read_b128 v[180:183], v235 offset:37888
	ds_read_b128 v[200:203], v235 offset:38912
	ds_read_b128 v[204:207], v235 offset:39936
	global_load_lds_dwordx4 v[216:217], off
	v_lshl_add_u64 v[216:217], s[42:43], 0, v[188:189]
	s_mov_b32 m0, s55
	s_nop 0
	global_load_lds_dwordx4 v[216:217], off
	s_waitcnt vmcnt(8)
	s_waitcnt lgkmcnt(0)
	s_barrier
	s_setprio 1
	s_waitcnt lgkmcnt(0)
	v_mfma_f32_16x16x32_bf16 v[128:131], v[120:123], v[160:163], v[128:131]
	v_mfma_f32_16x16x32_bf16 v[124:127], v[136:139], v[160:163], v[124:127]
	v_mfma_f32_16x16x32_bf16 v[108:111], v[120:123], v[168:171], v[108:111]
	v_mfma_f32_16x16x32_bf16 v[104:107], v[136:139], v[168:171], v[104:107]
	v_mfma_f32_16x16x32_bf16 v[92:95], v[120:123], v[176:179], v[92:95]
	v_mfma_f32_16x16x32_bf16 v[88:91], v[136:139], v[176:179], v[88:91]
	v_mfma_f32_16x16x32_bf16 v[76:79], v[120:123], v[200:203], v[76:79]
	v_mfma_f32_16x16x32_bf16 v[72:75], v[136:139], v[200:203], v[72:75]
	v_mfma_f32_16x16x32_bf16 v[128:131], v[132:135], v[164:167], v[128:131]
	v_mfma_f32_16x16x32_bf16 v[124:127], v[140:143], v[164:167], v[124:127]
	v_mfma_f32_16x16x32_bf16 v[108:111], v[132:135], v[172:175], v[108:111]
	v_mfma_f32_16x16x32_bf16 v[104:107], v[140:143], v[172:175], v[104:107]
	v_mfma_f32_16x16x32_bf16 v[92:95], v[132:135], v[180:183], v[92:95]
	v_mfma_f32_16x16x32_bf16 v[88:91], v[140:143], v[180:183], v[88:91]
	v_mfma_f32_16x16x32_bf16 v[76:79], v[132:135], v[204:207], v[76:79]
	v_mfma_f32_16x16x32_bf16 v[72:75], v[140:143], v[204:207], v[72:75]
	s_setprio 0
	s_setprio 1
	v_mfma_f32_16x16x32_bf16 v[116:119], v[144:147], v[160:163], v[116:119]
	v_mfma_f32_16x16x32_bf16 v[112:115], v[152:155], v[160:163], v[112:115]
	v_mfma_f32_16x16x32_bf16 v[100:103], v[144:147], v[168:171], v[100:103]
	v_mfma_f32_16x16x32_bf16 v[96:99], v[152:155], v[168:171], v[96:99]
	v_mfma_f32_16x16x32_bf16 v[84:87], v[144:147], v[176:179], v[84:87]
	v_mfma_f32_16x16x32_bf16 v[80:83], v[152:155], v[176:179], v[80:83]
	v_mfma_f32_16x16x32_bf16 v[68:71], v[144:147], v[200:203], v[68:71]
	v_mfma_f32_16x16x32_bf16 v[64:67], v[152:155], v[200:203], v[64:67]
	v_mfma_f32_16x16x32_bf16 v[116:119], v[148:151], v[164:167], v[116:119]
	v_mfma_f32_16x16x32_bf16 v[112:115], v[156:159], v[164:167], v[112:115]
	v_mfma_f32_16x16x32_bf16 v[100:103], v[148:151], v[172:175], v[100:103]
	v_mfma_f32_16x16x32_bf16 v[96:99], v[156:159], v[172:175], v[96:99]
	s_setprio 2
	s_barrier
	v_mfma_f32_16x16x32_bf16 v[84:87], v[148:151], v[180:183], v[84:87]
	v_mfma_f32_16x16x32_bf16 v[80:83], v[156:159], v[180:183], v[80:83]
	v_mfma_f32_16x16x32_bf16 v[68:71], v[148:151], v[204:207], v[68:71]
	v_mfma_f32_16x16x32_bf16 v[64:67], v[156:159], v[204:207], v[64:67]
	s_setprio 0
	s_add_i32 s42, s67, s49
	v_lshl_add_u64 v[208:209], v[208:209], 0, s[18:19]
	s_mov_b32 m0, s42
	ds_read_b128 v[160:163], v235 offset:49152
	ds_read_b128 v[164:167], v235 offset:50176
	ds_read_b128 v[168:171], v235 offset:51200
	ds_read_b128 v[172:175], v235 offset:52224
	ds_read_b128 v[176:179], v235 offset:53248
	ds_read_b128 v[180:183], v235 offset:54272
	ds_read_b128 v[200:203], v235 offset:55296
	ds_read_b128 v[204:207], v235 offset:56320
	global_load_lds_dwordx4 v[208:209], off
	s_add_i32 m0, s42, 0x2000
	s_add_u32 s40, s40, 0x40080
	v_lshl_add_u64 v[208:209], v[210:211], 0, s[18:19]
	s_addc_u32 s41, s41, 0
	s_add_i32 s42, s68, s49
	global_load_lds_dwordx4 v[208:209], off
	v_lshl_add_u64 v[208:209], s[40:41], 0, v[186:187]
	s_mov_b32 m0, s42
	s_nop 0
	global_load_lds_dwordx4 v[208:209], off
	v_lshl_add_u64 v[254:255], s[40:41], 0, v[190:191]
	s_add_i32 s99, s42, 0x2000
	v_lshl_add_u64 v[208:209], v[212:213], 0, s[18:19]
	s_mov_b32 m0, s57
	s_nop 0
	global_load_lds_dwordx4 v[208:209], off
	v_lshl_add_u64 v[208:209], v[214:215], 0, s[18:19]
	s_mov_b32 m0, s58
	s_nop 0
	global_load_lds_dwordx4 v[208:209], off
	s_waitcnt vmcnt(7)
	s_waitcnt lgkmcnt(0)
	s_barrier
	s_setprio 1
	s_waitcnt lgkmcnt(0)
	v_mfma_f32_16x16x32_bf16 v[60:63], v[120:123], v[160:163], v[60:63]
	v_mfma_f32_16x16x32_bf16 v[56:59], v[136:139], v[160:163], v[56:59]
	v_mfma_f32_16x16x32_bf16 v[44:47], v[120:123], v[168:171], v[44:47]
	v_mfma_f32_16x16x32_bf16 v[40:43], v[136:139], v[168:171], v[40:43]
	v_mfma_f32_16x16x32_bf16 v[28:31], v[120:123], v[176:179], v[28:31]
	v_mfma_f32_16x16x32_bf16 v[24:27], v[136:139], v[176:179], v[24:27]
	v_mfma_f32_16x16x32_bf16 v[12:15], v[120:123], v[200:203], v[12:15]
	v_mfma_f32_16x16x32_bf16 v[8:11], v[136:139], v[200:203], v[8:11]
	v_mfma_f32_16x16x32_bf16 v[60:63], v[132:135], v[164:167], v[60:63]
	v_mfma_f32_16x16x32_bf16 v[56:59], v[140:143], v[164:167], v[56:59]
	v_mfma_f32_16x16x32_bf16 v[44:47], v[132:135], v[172:175], v[44:47]
	v_mfma_f32_16x16x32_bf16 v[40:43], v[140:143], v[172:175], v[40:43]
	v_mfma_f32_16x16x32_bf16 v[28:31], v[132:135], v[180:183], v[28:31]
	v_mfma_f32_16x16x32_bf16 v[24:27], v[140:143], v[180:183], v[24:27]
	v_mfma_f32_16x16x32_bf16 v[12:15], v[132:135], v[204:207], v[12:15]
	v_mfma_f32_16x16x32_bf16 v[8:11], v[140:143], v[204:207], v[8:11]
	s_setprio 0
	s_setprio 1
	v_mfma_f32_16x16x32_bf16 v[52:55], v[144:147], v[160:163], v[52:55]
	v_mfma_f32_16x16x32_bf16 v[48:51], v[152:155], v[160:163], v[48:51]
	v_mfma_f32_16x16x32_bf16 v[36:39], v[144:147], v[168:171], v[36:39]
	v_mfma_f32_16x16x32_bf16 v[32:35], v[152:155], v[168:171], v[32:35]
	v_mfma_f32_16x16x32_bf16 v[20:23], v[144:147], v[176:179], v[20:23]
	v_mfma_f32_16x16x32_bf16 v[16:19], v[152:155], v[176:179], v[16:19]
	v_mfma_f32_16x16x32_bf16 v[4:7], v[144:147], v[200:203], v[4:7]
	v_mfma_f32_16x16x32_bf16 v[0:3], v[152:155], v[200:203], v[0:3]
	v_mfma_f32_16x16x32_bf16 v[52:55], v[148:151], v[164:167], v[52:55]
	v_mfma_f32_16x16x32_bf16 v[48:51], v[156:159], v[164:167], v[48:51]
	v_mfma_f32_16x16x32_bf16 v[36:39], v[148:151], v[172:175], v[36:39]
	v_mfma_f32_16x16x32_bf16 v[32:35], v[156:159], v[172:175], v[32:35]
	s_setprio 2
	s_barrier
	v_mfma_f32_16x16x32_bf16 v[20:23], v[148:151], v[180:183], v[20:23]
	v_mfma_f32_16x16x32_bf16 v[16:19], v[156:159], v[180:183], v[16:19]
	v_mfma_f32_16x16x32_bf16 v[4:7], v[148:151], v[204:207], v[4:7]
	v_mfma_f32_16x16x32_bf16 v[0:3], v[156:159], v[204:207], v[0:3]
	s_setprio 0
	s_add_i32 s66, s66, 2
	s_add_u32 s38, s38, 0x100
	s_addc_u32 s39, s39, 0
	s_add_u32 s64, s64, 0x100
	s_addc_u32 s65, s65, 0
	s_cmp_gt_u32 s66, 13
	s_cbranch_scc0 .LBB0_1146

.LBB0_1224:
	s_add_u32 s12, s4, 0x140000
	s_addc_u32 s13, s5, 0
	s_add_u32 s14, s4, 0x4800000
	s_addc_u32 s15, s5, 0
	s_lshl_b32 s56, s17, 6
	s_lshl_b32 s19, s17, 13
	s_lshl_b32 s4, s16, 5
	s_mov_b64 s[16:17], 0x80
	s_and_b32 s20, s4, 0x60
	s_add_i32 m0, s50, 0x18000
	v_lshl_add_u64 v[6:7], v[6:7], 0, s[16:17]
	s_lshl_b32 s22, s20, 7
	s_waitcnt vmcnt(2)
	s_barrier
	global_load_lds_dwordx4 v[6:7], off
	v_lshl_add_u64 v[4:5], v[4:5], 0, s[16:17]
	s_add_i32 m0, s50, 0x1a000
	s_add_i32 s57, s50, 0x8000
	s_add_i32 s58, s50, 0xa000
	global_load_lds_dwordx4 v[4:5], off
	v_lshl_add_u64 v[0:1], v[0:1], 0, s[16:17]
	s_mov_b32 m0, s57
	s_add_u32 s4, s38, 0x40080
	global_load_lds_dwordx4 v[0:1], off
	v_lshl_add_u64 v[0:1], v[2:3], 0, s[16:17]
	s_mov_b32 m0, s58
	s_addc_u32 s5, s39, 0
	global_load_lds_dwordx4 v[0:1], off
	s_add_i32 m0, s50, 0x1c000
	v_lshl_add_u64 v[0:1], s[4:5], 0, v[132:133]
	global_load_lds_dwordx4 v[0:1], off
	v_lshl_add_u64 v[0:1], s[4:5], 0, v[128:129]
	s_add_i32 m0, s50, 0x1e000
	s_movk_i32 s4, 0x3c0
	global_load_lds_dwordx4 v[0:1], off
	v_mov_b32_e32 v254, v0
	v_mov_b32_e32 v255, v1
	s_add_i32 s99, s50, 0x1e000
	v_and_b32_e32 v0, 48, v8
	v_lshlrev_b32_e32 v1, 6, v8
	v_and_or_b32 v0, v1, s4, v0
	v_lshlrev_b32_e32 v1, 2, v8
	v_and_b32_e32 v1, 32, v1
	v_bitop3_b32 v2, v0, s19, v1 bitop3:0xde
	v_bitop3_b32 v162, s22, v0, v1 bitop3:0xf6
	v_lshlrev_b32_e32 v0, 14, v13
	v_and_b32_e32 v0, 0xffff8000, v0
	v_lshl_add_u32 v0, v12, 11, v0
	v_and_b32_e32 v1, 1, v13
	v_lshl_or_b32 v0, v1, 6, v0
	v_lshl_add_u32 v136, v14, 1, v0
	v_lshlrev_b32_e32 v0, 14, v9
	v_and_b32_e32 v0, 0xffff8000, v0
	s_waitcnt vmcnt(6)
	s_cmpk_lt_u32 s18, 0x100
	v_lshl_add_u32 v0, v10, 11, v0
	v_and_b32_e32 v1, 1, v9
	s_cselect_b64 s[18:19], -1, 0
	v_lshl_or_b32 v0, v1, 6, v0
	s_add_i32 s59, 0, 0x10000
	s_add_i32 s60, 0, 0x14000
	s_sext_i32_i16 s21, s6
	v_mov_b32_e32 v137, v133
	v_lshl_add_u32 v138, v11, 1, v0
	v_mov_b32_e32 v139, v133
	v_mov_b64_e32 v[140:141], 0xb00
	v_mov_b64_e32 v[142:143], 0xaff
	v_add_u32_e32 v163, s59, v162
	v_add_u32_e32 v164, s60, v162
	v_add_u32_e32 v165, 0, v2
	v_mov_b32_e32 v166, 0x358637bd
	s_movk_i32 s61, 0x1600
	s_lshl_b32 s20, s20, 1
	s_mov_b32 s6, s7
	s_barrier
	s_branch .LBB0_1227

.LBB0_1296:
	s_lshl_b32 s1, s1, 5
	s_mov_b64 s[16:17], 0x80
	s_and_b32 s14, s1, 0x60
	s_add_i32 m0, s36, 0x18000
	v_lshl_add_u64 v[6:7], v[6:7], 0, s[16:17]
	s_lshl_b32 s40, s5, 6
	s_lshl_b32 s5, s5, 13
	s_lshl_b32 s1, s14, 7
	s_waitcnt vmcnt(2)
	s_barrier
	global_load_lds_dwordx4 v[6:7], off
	v_lshl_add_u64 v[4:5], v[4:5], 0, s[16:17]
	s_add_i32 m0, s36, 0x1a000
	s_add_i32 s41, s36, 0x8000
	s_add_i32 s42, s36, 0xa000
	global_load_lds_dwordx4 v[4:5], off
	v_lshl_add_u64 v[0:1], v[0:1], 0, s[16:17]
	s_mov_b32 m0, s41
	s_add_u32 s18, s26, 0xb0080
	global_load_lds_dwordx4 v[0:1], off
	v_lshl_add_u64 v[0:1], v[2:3], 0, s[16:17]
	s_mov_b32 m0, s42
	s_addc_u32 s19, s27, 0
	global_load_lds_dwordx4 v[0:1], off
	s_add_i32 m0, s36, 0x1c000
	v_lshl_add_u64 v[0:1], s[18:19], 0, v[166:167]
	global_load_lds_dwordx4 v[0:1], off
	v_lshl_add_u64 v[0:1], s[18:19], 0, v[170:171]
	s_add_i32 m0, s36, 0x1e000
	s_sext_i32_i8 s50, s4
	global_load_lds_dwordx4 v[0:1], off
	v_mov_b32_e32 v254, v0
	v_mov_b32_e32 v255, v1
	s_add_i32 s99, s36, 0x1e000
	v_and_b32_e32 v0, 48, v8
	v_lshlrev_b32_e32 v1, 6, v8
	s_movk_i32 s4, 0x3c0
	v_and_or_b32 v0, v1, s4, v0
	v_lshlrev_b32_e32 v1, 2, v8
	v_and_b32_e32 v1, 32, v1
	s_cmpk_lt_u32 s6, 0x100
	v_bitop3_b32 v196, s1, v0, v1 bitop3:0xf6
	s_cselect_b64 s[18:19], -1, 0
	s_lshl_b32 s1, s14, 1
	s_add_u32 s1, s10, s1
	s_addc_u32 s6, s11, 0
	v_bitop3_b32 v2, v0, s5, v1 bitop3:0xde
	s_add_u32 s43, s1, 0x14800000
	v_lshrrev_b32_e32 v1, 1, v9
	v_mul_lo_u32 v0, v11, s0
	s_mov_b32 s1, 0xb000
	v_mad_u64_u32 v[0:1], s[20:21], v1, s1, v[0:1]
	v_or_b32_e32 v0, v0, v10
	s_mov_b64 s[4:5], 0xb0080
	v_add_lshl_u32 v0, v0, v12, 1
	v_mov_b32_e32 v1, v167
	v_lshl_add_u64 v[172:173], v[0:1], 0, s[4:5]
	v_lshrrev_b32_e32 v1, 1, v13
	v_mul_lo_u32 v0, v14, s0
	s_addc_u32 s44, s6, 0
	v_mad_u64_u32 v[0:1], s[0:1], v1, s1, v[0:1]
	s_waitcnt vmcnt(6)
	s_cmp_lg_u64 s[8:9], 0
	v_or_b32_e32 v0, v0, v15
	s_cselect_b64 s[10:11], -1, 0
	v_add_lshl_u32 v0, v0, v16, 1
	v_mov_b32_e32 v1, v167
	s_add_i32 s45, 0, 0x10000
	s_add_i32 s46, 0, 0x14000
	s_mov_b32 s15, s7
	v_lshl_add_u64 v[174:175], v[0:1], 0, s[4:5]
	v_mov_b64_e32 v[176:177], 0x200
	v_mov_b64_e32 v[178:179], 0x1ff
	v_add_u32_e32 v197, s45, v196
	v_add_u32_e32 v198, s46, v196
	v_add_u32_e32 v199, 0, v2
	s_mov_b32 s6, s7
	s_barrier
	s_branch .LBB0_1299

.LBB0_1310:
	s_mov_b32 m0, s99
	s_nop 0
	global_load_lds_dwordx4 v[254:255], off
	ds_read_b128 v[128:131], v197
	ds_read_b128 v[132:135], v197 offset:1024
	ds_read_b128 v[136:139], v197 offset:2048
	ds_read_b128 v[140:143], v197 offset:3072
	ds_read_b128 v[144:147], v198
	ds_read_b128 v[148:151], v198 offset:1024
	ds_read_b128 v[152:155], v198 offset:2048
	ds_read_b128 v[156:159], v198 offset:3072
	s_add_u32 s4, s24, 0x100
	s_addc_u32 s5, s25, 0
	s_cmp_eq_u32 s53, 40
	s_cselect_b32 s29, s21, s5
	s_cselect_b32 s28, s20, s4
	s_cselect_b32 s27, s23, s52
	s_cselect_b32 s26, s22, s51
	v_lshl_add_u64 v[212:213], s[24:25], 0, v[172:173]
	s_add_i32 m0, s36, 0xc000
	ds_read_b128 v[160:163], v199
	ds_read_b128 v[180:183], v199 offset:1024
	ds_read_b128 v[184:187], v199 offset:2048
	ds_read_b128 v[188:191], v199 offset:3072
	ds_read_b128 v[192:195], v199 offset:4096
	ds_read_b128 v[200:203], v199 offset:5120
	ds_read_b128 v[204:207], v199 offset:6144
	ds_read_b128 v[208:211], v199 offset:7168
	global_load_lds_dwordx4 v[212:213], off
	v_lshl_add_u64 v[212:213], s[24:25], 0, v[174:175]
	s_add_i32 m0, s36, 0xe000
	s_nop 0
	global_load_lds_dwordx4 v[212:213], off
	s_waitcnt vmcnt(8)
	s_waitcnt lgkmcnt(0)
	s_barrier
	s_setprio 1
	s_waitcnt lgkmcnt(0)
	v_mfma_f32_16x16x32_bf16 v[124:127], v[128:131], v[160:163], v[124:127]
	v_mfma_f32_16x16x32_bf16 v[120:123], v[136:139], v[160:163], v[120:123]
	v_mfma_f32_16x16x32_bf16 v[116:119], v[128:131], v[184:187], v[116:119]
	v_mfma_f32_16x16x32_bf16 v[108:111], v[136:139], v[184:187], v[108:111]
	v_mfma_f32_16x16x32_bf16 v[88:91], v[128:131], v[192:195], v[88:91]
	v_mfma_f32_16x16x32_bf16 v[100:103], v[136:139], v[192:195], v[100:103]
	v_mfma_f32_16x16x32_bf16 v[72:75], v[128:131], v[204:207], v[72:75]
	v_mfma_f32_16x16x32_bf16 v[76:79], v[136:139], v[204:207], v[76:79]
	v_mfma_f32_16x16x32_bf16 v[124:127], v[132:135], v[180:183], v[124:127]
	v_mfma_f32_16x16x32_bf16 v[120:123], v[140:143], v[180:183], v[120:123]
	v_mfma_f32_16x16x32_bf16 v[116:119], v[132:135], v[188:191], v[116:119]
	v_mfma_f32_16x16x32_bf16 v[108:111], v[140:143], v[188:191], v[108:111]
	v_mfma_f32_16x16x32_bf16 v[88:91], v[132:135], v[200:203], v[88:91]
	v_mfma_f32_16x16x32_bf16 v[100:103], v[140:143], v[200:203], v[100:103]
	v_mfma_f32_16x16x32_bf16 v[72:75], v[132:135], v[208:211], v[72:75]
	v_mfma_f32_16x16x32_bf16 v[76:79], v[140:143], v[208:211], v[76:79]
	s_setprio 0
	s_setprio 1
	v_mfma_f32_16x16x32_bf16 v[112:115], v[144:147], v[160:163], v[112:115]
	v_mfma_f32_16x16x32_bf16 v[104:107], v[152:155], v[160:163], v[104:107]
	v_mfma_f32_16x16x32_bf16 v[96:99], v[144:147], v[184:187], v[96:99]
	v_mfma_f32_16x16x32_bf16 v[92:95], v[152:155], v[184:187], v[92:95]
	v_mfma_f32_16x16x32_bf16 v[80:83], v[144:147], v[192:195], v[80:83]
	v_mfma_f32_16x16x32_bf16 v[84:87], v[152:155], v[192:195], v[84:87]
	v_mfma_f32_16x16x32_bf16 v[64:67], v[144:147], v[204:207], v[64:67]
	v_mfma_f32_16x16x32_bf16 v[68:71], v[152:155], v[204:207], v[68:71]
	v_mfma_f32_16x16x32_bf16 v[112:115], v[148:151], v[180:183], v[112:115]
	v_mfma_f32_16x16x32_bf16 v[104:107], v[156:159], v[180:183], v[104:107]
	v_mfma_f32_16x16x32_bf16 v[96:99], v[148:151], v[188:191], v[96:99]
	v_mfma_f32_16x16x32_bf16 v[92:95], v[156:159], v[188:191], v[92:95]
	s_setprio 2
	s_barrier
	v_mfma_f32_16x16x32_bf16 v[80:83], v[148:151], v[200:203], v[80:83]
	v_mfma_f32_16x16x32_bf16 v[84:87], v[156:159], v[200:203], v[84:87]
	v_mfma_f32_16x16x32_bf16 v[64:67], v[148:151], v[208:211], v[64:67]
	v_mfma_f32_16x16x32_bf16 v[68:71], v[156:159], v[208:211], v[68:71]
	s_setprio 0
	s_add_i32 s24, s45, s35
	v_lshl_add_u64 v[212:213], s[26:27], 0, v[166:167]
	s_mov_b32 m0, s24
	ds_read_b128 v[160:163], v199 offset:16384
	ds_read_b128 v[180:183], v199 offset:17408
	ds_read_b128 v[184:187], v199 offset:18432
	ds_read_b128 v[188:191], v199 offset:19456
	ds_read_b128 v[192:195], v199 offset:20480
	ds_read_b128 v[200:203], v199 offset:21504
	ds_read_b128 v[204:207], v199 offset:22528
	ds_read_b128 v[208:211], v199 offset:23552
	global_load_lds_dwordx4 v[212:213], off
	s_add_i32 m0, s24, 0x2000
	s_add_u32 s24, s26, 0xb0000
	v_lshl_add_u64 v[214:215], s[26:27], 0, v[170:171]
	s_addc_u32 s25, s27, 0
	s_add_i32 s54, s46, s35
	global_load_lds_dwordx4 v[214:215], off
	v_lshl_add_u64 v[216:217], s[24:25], 0, v[166:167]
	s_mov_b32 m0, s54
	v_lshl_add_u64 v[218:219], s[28:29], 0, v[168:169]
	global_load_lds_dwordx4 v[216:217], off
	v_lshl_add_u64 v[216:217], s[28:29], 0, v[164:165]
	s_mov_b32 m0, s36
	s_nop 0
	global_load_lds_dwordx4 v[216:217], off
	s_mov_b32 m0, s37
	s_nop 0
	global_load_lds_dwordx4 v[218:219], off
	s_waitcnt vmcnt(7)
	s_waitcnt lgkmcnt(0)
	s_barrier
	s_setprio 1
	s_waitcnt lgkmcnt(0)
	v_mfma_f32_16x16x32_bf16 v[56:59], v[128:131], v[160:163], v[56:59]
	v_mfma_f32_16x16x32_bf16 v[60:63], v[136:139], v[160:163], v[60:63]
	v_mfma_f32_16x16x32_bf16 v[40:43], v[128:131], v[184:187], v[40:43]
	v_mfma_f32_16x16x32_bf16 v[44:47], v[136:139], v[184:187], v[44:47]
	v_mfma_f32_16x16x32_bf16 v[24:27], v[128:131], v[192:195], v[24:27]
	v_mfma_f32_16x16x32_bf16 v[28:31], v[136:139], v[192:195], v[28:31]
	v_mfma_f32_16x16x32_bf16 v[8:11], v[128:131], v[204:207], v[8:11]
	v_mfma_f32_16x16x32_bf16 v[12:15], v[136:139], v[204:207], v[12:15]
	v_mfma_f32_16x16x32_bf16 v[56:59], v[132:135], v[180:183], v[56:59]
	v_mfma_f32_16x16x32_bf16 v[60:63], v[140:143], v[180:183], v[60:63]
	v_mfma_f32_16x16x32_bf16 v[40:43], v[132:135], v[188:191], v[40:43]
	v_mfma_f32_16x16x32_bf16 v[44:47], v[140:143], v[188:191], v[44:47]
	v_mfma_f32_16x16x32_bf16 v[24:27], v[132:135], v[200:203], v[24:27]
	v_mfma_f32_16x16x32_bf16 v[28:31], v[140:143], v[200:203], v[28:31]
	v_mfma_f32_16x16x32_bf16 v[8:11], v[132:135], v[208:211], v[8:11]
	v_mfma_f32_16x16x32_bf16 v[12:15], v[140:143], v[208:211], v[12:15]
	s_setprio 0
	s_setprio 1
	v_mfma_f32_16x16x32_bf16 v[48:51], v[144:147], v[160:163], v[48:51]
	v_mfma_f32_16x16x32_bf16 v[52:55], v[152:155], v[160:163], v[52:55]
	v_mfma_f32_16x16x32_bf16 v[32:35], v[144:147], v[184:187], v[32:35]
	v_mfma_f32_16x16x32_bf16 v[36:39], v[152:155], v[184:187], v[36:39]
	v_mfma_f32_16x16x32_bf16 v[16:19], v[144:147], v[192:195], v[16:19]
	v_mfma_f32_16x16x32_bf16 v[20:23], v[152:155], v[192:195], v[20:23]
	v_mfma_f32_16x16x32_bf16 v[0:3], v[144:147], v[204:207], v[0:3]
	v_mfma_f32_16x16x32_bf16 v[4:7], v[152:155], v[204:207], v[4:7]
	v_mfma_f32_16x16x32_bf16 v[48:51], v[148:151], v[180:183], v[48:51]
	v_mfma_f32_16x16x32_bf16 v[52:55], v[156:159], v[180:183], v[52:55]
	v_mfma_f32_16x16x32_bf16 v[32:35], v[148:151], v[188:191], v[32:35]
	v_mfma_f32_16x16x32_bf16 v[36:39], v[156:159], v[188:191], v[36:39]
	s_setprio 2
	s_barrier
	v_mfma_f32_16x16x32_bf16 v[16:19], v[148:151], v[200:203], v[16:19]
	v_mfma_f32_16x16x32_bf16 v[20:23], v[156:159], v[200:203], v[20:23]
	v_mfma_f32_16x16x32_bf16 v[0:3], v[148:151], v[208:211], v[0:3]
	v_mfma_f32_16x16x32_bf16 v[4:7], v[156:159], v[208:211], v[4:7]
	s_setprio 0
	v_lshl_add_u64 v[252:253], s[24:25], 0, v[170:171]
	s_add_i32 m0, s54, 0x2000
	s_nop 0
	global_load_lds_dwordx4 v[252:253], off
	s_add_i32 s54, 0, 0x18000
	s_add_i32 s55, 0, 0x1c000
	v_add_u32_e32 v140, s54, v196
	v_add_u32_e32 v156, s55, v196
	ds_read_b128 v[128:131], v140
	ds_read_b128 v[132:135], v140 offset:1024
	ds_read_b128 v[136:139], v140 offset:2048
	ds_read_b128 v[140:143], v140 offset:3072
	ds_read_b128 v[144:147], v156
	ds_read_b128 v[148:151], v156 offset:1024
	ds_read_b128 v[152:155], v156 offset:2048
	ds_read_b128 v[156:159], v156 offset:3072
	s_add_u32 s24, s28, 0xb0000
	s_addc_u32 s25, s29, 0
	s_mov_b32 m0, s38
	v_lshl_add_u64 v[220:221], s[24:25], 0, v[164:165]
	ds_read_b128 v[160:163], v199 offset:32768
	ds_read_b128 v[180:183], v199 offset:33792
	ds_read_b128 v[184:187], v199 offset:34816
	ds_read_b128 v[188:191], v199 offset:35840
	ds_read_b128 v[192:195], v199 offset:36864
	ds_read_b128 v[200:203], v199 offset:37888
	ds_read_b128 v[204:207], v199 offset:38912
	ds_read_b128 v[208:211], v199 offset:39936
	global_load_lds_dwordx4 v[220:221], off
	v_lshl_add_u64 v[220:221], s[24:25], 0, v[168:169]
	s_mov_b32 m0, s39
	s_nop 0
	global_load_lds_dwordx4 v[220:221], off
	s_waitcnt vmcnt(8)
	s_waitcnt lgkmcnt(0)
	s_barrier
	s_setprio 1
	s_waitcnt lgkmcnt(0)
	v_mfma_f32_16x16x32_bf16 v[124:127], v[128:131], v[160:163], v[124:127]
	v_mfma_f32_16x16x32_bf16 v[120:123], v[136:139], v[160:163], v[120:123]
	v_mfma_f32_16x16x32_bf16 v[116:119], v[128:131], v[184:187], v[116:119]
	v_mfma_f32_16x16x32_bf16 v[108:111], v[136:139], v[184:187], v[108:111]
	v_mfma_f32_16x16x32_bf16 v[88:91], v[128:131], v[192:195], v[88:91]
	v_mfma_f32_16x16x32_bf16 v[100:103], v[136:139], v[192:195], v[100:103]
	v_mfma_f32_16x16x32_bf16 v[72:75], v[128:131], v[204:207], v[72:75]
	v_mfma_f32_16x16x32_bf16 v[76:79], v[136:139], v[204:207], v[76:79]
	v_mfma_f32_16x16x32_bf16 v[124:127], v[132:135], v[180:183], v[124:127]
	v_mfma_f32_16x16x32_bf16 v[120:123], v[140:143], v[180:183], v[120:123]
	v_mfma_f32_16x16x32_bf16 v[116:119], v[132:135], v[188:191], v[116:119]
	v_mfma_f32_16x16x32_bf16 v[108:111], v[140:143], v[188:191], v[108:111]
	v_mfma_f32_16x16x32_bf16 v[88:91], v[132:135], v[200:203], v[88:91]
	v_mfma_f32_16x16x32_bf16 v[100:103], v[140:143], v[200:203], v[100:103]
	v_mfma_f32_16x16x32_bf16 v[72:75], v[132:135], v[208:211], v[72:75]
	v_mfma_f32_16x16x32_bf16 v[76:79], v[140:143], v[208:211], v[76:79]
	s_setprio 0
	s_setprio 1
	v_mfma_f32_16x16x32_bf16 v[112:115], v[144:147], v[160:163], v[112:115]
	v_mfma_f32_16x16x32_bf16 v[104:107], v[152:155], v[160:163], v[104:107]
	v_mfma_f32_16x16x32_bf16 v[96:99], v[144:147], v[184:187], v[96:99]
	v_mfma_f32_16x16x32_bf16 v[92:95], v[152:155], v[184:187], v[92:95]
	v_mfma_f32_16x16x32_bf16 v[80:83], v[144:147], v[192:195], v[80:83]
	v_mfma_f32_16x16x32_bf16 v[84:87], v[152:155], v[192:195], v[84:87]
	v_mfma_f32_16x16x32_bf16 v[64:67], v[144:147], v[204:207], v[64:67]
	v_mfma_f32_16x16x32_bf16 v[68:71], v[152:155], v[204:207], v[68:71]
	v_mfma_f32_16x16x32_bf16 v[112:115], v[148:151], v[180:183], v[112:115]
	v_mfma_f32_16x16x32_bf16 v[104:107], v[156:159], v[180:183], v[104:107]
	v_mfma_f32_16x16x32_bf16 v[96:99], v[148:151], v[188:191], v[96:99]
	v_mfma_f32_16x16x32_bf16 v[92:95], v[156:159], v[188:191], v[92:95]
	s_setprio 2
	s_barrier
	v_mfma_f32_16x16x32_bf16 v[80:83], v[148:151], v[200:203], v[80:83]
	v_mfma_f32_16x16x32_bf16 v[84:87], v[156:159], v[200:203], v[84:87]
	v_mfma_f32_16x16x32_bf16 v[64:67], v[148:151], v[208:211], v[64:67]
	v_mfma_f32_16x16x32_bf16 v[68:71], v[156:159], v[208:211], v[68:71]
	s_setprio 0
	s_add_i32 s24, s54, s35
	v_lshl_add_u64 v[212:213], v[212:213], 0, s[16:17]
	s_mov_b32 m0, s24
	ds_read_b128 v[160:163], v199 offset:49152
	ds_read_b128 v[180:183], v199 offset:50176
	ds_read_b128 v[184:187], v199 offset:51200
	ds_read_b128 v[188:191], v199 offset:52224
	ds_read_b128 v[192:195], v199 offset:53248
	ds_read_b128 v[200:203], v199 offset:54272
	ds_read_b128 v[204:207], v199 offset:55296
	ds_read_b128 v[208:211], v199 offset:56320
	global_load_lds_dwordx4 v[212:213], off
	s_add_i32 m0, s24, 0x2000
	s_add_u32 s24, s26, 0xb0080
	v_lshl_add_u64 v[212:213], v[214:215], 0, s[16:17]
	s_addc_u32 s25, s27, 0
	s_add_i32 s26, s55, s35
	global_load_lds_dwordx4 v[212:213], off
	v_lshl_add_u64 v[212:213], s[24:25], 0, v[166:167]
	s_mov_b32 m0, s26
	s_nop 0
	global_load_lds_dwordx4 v[212:213], off
	v_lshl_add_u64 v[254:255], s[24:25], 0, v[170:171]
	s_add_i32 s99, s26, 0x2000
	v_lshl_add_u64 v[212:213], v[216:217], 0, s[16:17]
	s_mov_b32 m0, s41
	s_nop 0
	global_load_lds_dwordx4 v[212:213], off
	v_lshl_add_u64 v[212:213], v[218:219], 0, s[16:17]
	s_mov_b32 m0, s42
	s_nop 0
	global_load_lds_dwordx4 v[212:213], off
	s_waitcnt vmcnt(7)
	s_waitcnt lgkmcnt(0)
	s_barrier
	s_setprio 1
	s_waitcnt lgkmcnt(0)
	v_mfma_f32_16x16x32_bf16 v[56:59], v[128:131], v[160:163], v[56:59]
	v_mfma_f32_16x16x32_bf16 v[60:63], v[136:139], v[160:163], v[60:63]
	v_mfma_f32_16x16x32_bf16 v[40:43], v[128:131], v[184:187], v[40:43]
	v_mfma_f32_16x16x32_bf16 v[44:47], v[136:139], v[184:187], v[44:47]
	v_mfma_f32_16x16x32_bf16 v[24:27], v[128:131], v[192:195], v[24:27]
	v_mfma_f32_16x16x32_bf16 v[28:31], v[136:139], v[192:195], v[28:31]
	v_mfma_f32_16x16x32_bf16 v[8:11], v[128:131], v[204:207], v[8:11]
	v_mfma_f32_16x16x32_bf16 v[12:15], v[136:139], v[204:207], v[12:15]
	v_mfma_f32_16x16x32_bf16 v[56:59], v[132:135], v[180:183], v[56:59]
	v_mfma_f32_16x16x32_bf16 v[60:63], v[140:143], v[180:183], v[60:63]
	v_mfma_f32_16x16x32_bf16 v[40:43], v[132:135], v[188:191], v[40:43]
	v_mfma_f32_16x16x32_bf16 v[44:47], v[140:143], v[188:191], v[44:47]
	v_mfma_f32_16x16x32_bf16 v[24:27], v[132:135], v[200:203], v[24:27]
	v_mfma_f32_16x16x32_bf16 v[28:31], v[140:143], v[200:203], v[28:31]
	v_mfma_f32_16x16x32_bf16 v[8:11], v[132:135], v[208:211], v[8:11]
	v_mfma_f32_16x16x32_bf16 v[12:15], v[140:143], v[208:211], v[12:15]
	s_setprio 0
	s_setprio 1
	v_mfma_f32_16x16x32_bf16 v[48:51], v[144:147], v[160:163], v[48:51]
	v_mfma_f32_16x16x32_bf16 v[52:55], v[152:155], v[160:163], v[52:55]
	v_mfma_f32_16x16x32_bf16 v[32:35], v[144:147], v[184:187], v[32:35]
	v_mfma_f32_16x16x32_bf16 v[36:39], v[152:155], v[184:187], v[36:39]
	v_mfma_f32_16x16x32_bf16 v[16:19], v[144:147], v[192:195], v[16:19]
	v_mfma_f32_16x16x32_bf16 v[20:23], v[152:155], v[192:195], v[20:23]
	v_mfma_f32_16x16x32_bf16 v[0:3], v[144:147], v[204:207], v[0:3]
	v_mfma_f32_16x16x32_bf16 v[4:7], v[152:155], v[204:207], v[4:7]
	v_mfma_f32_16x16x32_bf16 v[48:51], v[148:151], v[180:183], v[48:51]
	v_mfma_f32_16x16x32_bf16 v[52:55], v[156:159], v[180:183], v[52:55]
	v_mfma_f32_16x16x32_bf16 v[32:35], v[148:151], v[188:191], v[32:35]
	v_mfma_f32_16x16x32_bf16 v[36:39], v[156:159], v[188:191], v[36:39]
	s_setprio 2
	s_barrier
	v_mfma_f32_16x16x32_bf16 v[16:19], v[148:151], v[200:203], v[16:19]
	v_mfma_f32_16x16x32_bf16 v[20:23], v[156:159], v[200:203], v[20:23]
	v_mfma_f32_16x16x32_bf16 v[0:3], v[148:151], v[208:211], v[0:3]
	v_mfma_f32_16x16x32_bf16 v[4:7], v[156:159], v[208:211], v[4:7]
	s_setprio 0
	s_add_i32 s53, s53, 2
	s_add_u32 s51, s51, 0x100
	s_addc_u32 s52, s52, 0
	s_cmp_gt_u32 s53, 41
	s_mov_b64 s[24:25], s[4:5]
	s_cbranch_scc0 .LBB0_1310

	.amdhsa_kernel _Z4mega5MArgs
		.amdhsa_group_segment_fixed_size 0
		.amdhsa_private_segment_fixed_size 0
		.amdhsa_kernarg_size 424
		.amdhsa_user_sgpr_count 2
		.amdhsa_user_sgpr_dispatch_ptr 0
		.amdhsa_user_sgpr_queue_ptr 0
		.amdhsa_user_sgpr_kernarg_segment_ptr 1
		.amdhsa_user_sgpr_dispatch_id 0
		.amdhsa_user_sgpr_kernarg_preload_length 0
		.amdhsa_user_sgpr_kernarg_preload_offset 0
		.amdhsa_user_sgpr_private_segment_size 0
		.amdhsa_uses_dynamic_stack 0
		.amdhsa_enable_private_segment 0
		.amdhsa_system_sgpr_workgroup_id_x 1
		.amdhsa_system_sgpr_workgroup_id_y 0
		.amdhsa_system_sgpr_workgroup_id_z 0
		.amdhsa_system_sgpr_workgroup_info 0
		.amdhsa_system_vgpr_workitem_id 0
		.amdhsa_next_free_vgpr 256
		.amdhsa_next_free_sgpr 100
		.amdhsa_accum_offset 256
		.amdhsa_reserve_vcc 1
		.amdhsa_float_round_mode_32 0
		.amdhsa_float_round_mode_16_64 0
		.amdhsa_float_denorm_mode_32 3
		.amdhsa_float_denorm_mode_16_64 3
		.amdhsa_dx10_clamp 1
		.amdhsa_ieee_mode 1
		.amdhsa_fp16_overflow 0
		.amdhsa_tg_split 0
		.amdhsa_exception_fp_ieee_invalid_op 0
		.amdhsa_exception_fp_denorm_src 0
		.amdhsa_exception_fp_ieee_div_zero 0
		.amdhsa_exception_fp_ieee_overflow 0
		.amdhsa_exception_fp_ieee_underflow 0
		.amdhsa_exception_fp_ieee_inexact 0
		.amdhsa_exception_int_div_zero 0
	.end_amdhsa_kernel

amdhsa.kernels:
  - .agpr_count:     0
    .args:
      - .offset:         0
        .size:           168
        .value_kind:     by_value
      - .offset:         168
        .size:           4
        .value_kind:     hidden_block_count_x
      - .offset:         172
        .size:           4
        .value_kind:     hidden_block_count_y
      - .offset:         176
        .size:           4
        .value_kind:     hidden_block_count_z
      - .offset:         180
        .size:           2
        .value_kind:     hidden_group_size_x
      - .offset:         182
        .size:           2
        .value_kind:     hidden_group_size_y
      - .offset:         184
        .size:           2
        .value_kind:     hidden_group_size_z
      - .offset:         186
        .size:           2
        .value_kind:     hidden_remainder_x
      - .offset:         188
        .size:           2
        .value_kind:     hidden_remainder_y
      - .offset:         190
        .size:           2
        .value_kind:     hidden_remainder_z
      - .offset:         208
        .size:           8
        .value_kind:     hidden_global_offset_x
      - .offset:         216
        .size:           8
        .value_kind:     hidden_global_offset_y
      - .offset:         224
        .size:           8
        .value_kind:     hidden_global_offset_z
      - .offset:         232
        .size:           2
        .value_kind:     hidden_grid_dims
      - .offset:         288
        .size:           4
        .value_kind:     hidden_dynamic_lds_size
    .group_segment_fixed_size: 0
    .kernarg_segment_align: 8
    .kernarg_segment_size: 424
    .language:       OpenCL C
    .language_version:
      - 2
      - 0
    .max_flat_workgroup_size: 512
    .name:           _Z4mega5MArgs
    .private_segment_fixed_size: 0
    .sgpr_count:     106
    .sgpr_spill_count: 8
    .symbol:         _Z4mega5MArgs.kd
    .uniform_work_group_size: 1
    .uses_dynamic_stack: false
    .vgpr_count:     256
    .vgpr_spill_count: 0
    .wavefront_size: 64
